# on top of epilogue hoists: all s_setprio flips removed from the six GEMM K-loops (timing-only)
# speedup vs baseline: 1.0003x; 1.0003x over previous
.LBB0_341:
	v_add_u32_e32 v2, s41, v173
	s_waitcnt lgkmcnt(0)
	ds_read_b128 v[142:145], v2
	ds_read_b128 v[146:149], v2 offset:1024
	ds_read_b128 v[150:153], v2 offset:2048
	ds_read_b128 v[154:157], v2 offset:3072
	v_add_u32_e32 v2, s82, v173
	ds_read_b128 v[158:161], v2
	ds_read_b128 v[162:165], v2 offset:1024
	ds_read_b128 v[166:169], v2 offset:2048
	ds_read_b128 v[180:183], v2 offset:3072
	s_add_i32 s21, s14, 2
	s_add_u32 s16, s12, 0x80
	s_addc_u32 s15, s13, 0
	s_cmp_eq_u32 s18, s14
	s_cselect_b32 s14, s60, s16
	s_cselect_b32 s66, s58, s4
	s_cselect_b32 s15, s61, s15
	s_cselect_b32 s22, s63, s7
	s_cselect_b32 s23, s62, s6
	s_cselect_b32 s17, s65, s20
	s_cselect_b32 s16, s64, s19
	v_lshl_add_u64 v[218:219], s[12:13], 0, v[140:141]
	s_add_i32 m0, s55, 0xc000
	ds_read_b128 v[184:187], v176
	ds_read_b128 v[188:191], v176 offset:1024
	ds_read_b128 v[192:195], v176 offset:2048
	ds_read_b128 v[196:199], v176 offset:3072
	ds_read_b128 v[200:203], v176 offset:4096
	ds_read_b128 v[204:207], v176 offset:5120
	ds_read_b128 v[210:213], v176 offset:6144
	ds_read_b128 v[214:217], v176 offset:7168
	global_load_lds_dwordx4 v[218:219], off
	v_lshl_add_u64 v[218:219], s[12:13], 0, v[4:5]
	s_add_i32 m0, s55, 0xe000
	s_nop 0
	global_load_lds_dwordx4 v[218:219], off
	s_waitcnt vmcnt(8)
	s_waitcnt lgkmcnt(0)
	s_barrier
	s_waitcnt lgkmcnt(0)
	v_mfma_f32_16x16x32_bf16 v[130:133], v[142:145], v[184:187], v[130:133]
	v_mfma_f32_16x16x32_bf16 v[126:129], v[150:153], v[184:187], v[126:129]
	v_mfma_f32_16x16x32_bf16 v[122:125], v[142:145], v[192:195], v[122:125]
	v_mfma_f32_16x16x32_bf16 v[118:121], v[150:153], v[192:195], v[118:121]
	v_mfma_f32_16x16x32_bf16 v[114:117], v[142:145], v[200:203], v[114:117]
	v_mfma_f32_16x16x32_bf16 v[110:113], v[150:153], v[200:203], v[110:113]
	v_mfma_f32_16x16x32_bf16 v[106:109], v[142:145], v[210:213], v[106:109]
	v_mfma_f32_16x16x32_bf16 v[102:105], v[150:153], v[210:213], v[102:105]
	v_mfma_f32_16x16x32_bf16 v[130:133], v[146:149], v[188:191], v[130:133]
	v_mfma_f32_16x16x32_bf16 v[126:129], v[154:157], v[188:191], v[126:129]
	v_mfma_f32_16x16x32_bf16 v[122:125], v[146:149], v[196:199], v[122:125]
	v_mfma_f32_16x16x32_bf16 v[118:121], v[154:157], v[196:199], v[118:121]
	v_mfma_f32_16x16x32_bf16 v[114:117], v[146:149], v[204:207], v[114:117]
	v_mfma_f32_16x16x32_bf16 v[110:113], v[154:157], v[204:207], v[110:113]
	v_mfma_f32_16x16x32_bf16 v[106:109], v[146:149], v[214:217], v[106:109]
	v_mfma_f32_16x16x32_bf16 v[102:105], v[154:157], v[214:217], v[102:105]
	v_mfma_f32_16x16x32_bf16 v[98:101], v[158:161], v[184:187], v[98:101]
	v_mfma_f32_16x16x32_bf16 v[94:97], v[166:169], v[184:187], v[94:97]
	v_mfma_f32_16x16x32_bf16 v[90:93], v[158:161], v[192:195], v[90:93]
	v_mfma_f32_16x16x32_bf16 v[86:89], v[166:169], v[192:195], v[86:89]
	v_mfma_f32_16x16x32_bf16 v[82:85], v[158:161], v[200:203], v[82:85]
	v_mfma_f32_16x16x32_bf16 v[78:81], v[166:169], v[200:203], v[78:81]
	v_mfma_f32_16x16x32_bf16 v[74:77], v[158:161], v[210:213], v[74:77]
	v_mfma_f32_16x16x32_bf16 v[70:73], v[166:169], v[210:213], v[70:73]
	v_mfma_f32_16x16x32_bf16 v[98:101], v[162:165], v[188:191], v[98:101]
	v_mfma_f32_16x16x32_bf16 v[94:97], v[180:183], v[188:191], v[94:97]
	v_mfma_f32_16x16x32_bf16 v[90:93], v[162:165], v[196:199], v[90:93]
	v_mfma_f32_16x16x32_bf16 v[86:89], v[180:183], v[196:199], v[86:89]
	v_mfma_f32_16x16x32_bf16 v[82:85], v[162:165], v[204:207], v[82:85]
	v_mfma_f32_16x16x32_bf16 v[78:81], v[180:183], v[204:207], v[78:81]
	v_mfma_f32_16x16x32_bf16 v[74:77], v[162:165], v[214:217], v[74:77]
	v_mfma_f32_16x16x32_bf16 v[70:73], v[180:183], v[214:217], v[70:73]
	s_barrier
	s_add_i32 s70, s41, s5
	v_mad_u64_u32 v[218:219], s[50:51], s66, v137, v[136:137]
	s_mov_b32 m0, s70
	v_mad_u64_u32 v[222:223], s[50:51], s66, v170, v[136:137]
	ds_read_b128 v[184:187], v176 offset:16384
	ds_read_b128 v[188:191], v176 offset:17408
	ds_read_b128 v[192:195], v176 offset:18432
	ds_read_b128 v[196:199], v176 offset:19456
	ds_read_b128 v[200:203], v176 offset:20480
	ds_read_b128 v[204:207], v176 offset:21504
	ds_read_b128 v[210:213], v176 offset:22528
	ds_read_b128 v[214:217], v176 offset:23552
	v_mov_b32_e32 v219, v3
	global_load_lds_dwordx4 v218, s[16:17]
	v_mov_b32_e32 v223, v3
	s_add_i32 m0, s70, 0x2000
	v_lshl_add_u64 v[220:221], s[16:17], 0, v[218:219]
	v_lshl_add_u64 v[224:225], s[16:17], 0, v[222:223]
	global_load_lds_dwordx4 v222, s[16:17]
	s_add_u32 s16, s16, s23
	s_addc_u32 s17, s17, s22
	s_add_i32 s50, s82, s5
	s_mov_b32 m0, s50
	v_lshl_add_u64 v[226:227], s[16:17], 0, v[218:219]
	global_load_lds_dwordx4 v218, s[16:17]
	s_add_i32 m0, s50, 0x2000
	v_lshl_add_u64 v[218:219], s[16:17], 0, v[222:223]
	global_load_lds_dwordx4 v222, s[16:17]
	v_mad_u64_u32 v[222:223], s[16:17], s66, v135, v[136:137]
	s_mov_b32 m0, s55
	v_mad_u64_u32 v[230:231], s[16:17], s66, v139, v[136:137]
	global_load_lds_dwordx4 v222, s[14:15]
	s_mov_b32 m0, s56
	v_mov_b32_e32 v223, v3
	global_load_lds_dwordx4 v230, s[14:15]
	s_waitcnt vmcnt(8)
	s_waitcnt lgkmcnt(0)
	v_mov_b32_e32 v231, v3
	v_lshl_add_u64 v[228:229], s[14:15], 0, v[222:223]
	v_lshl_add_u64 v[232:233], s[14:15], 0, v[230:231]
	s_barrier
	s_waitcnt lgkmcnt(0)
	v_mfma_f32_16x16x32_bf16 v[66:69], v[142:145], v[184:187], v[66:69]
	v_mfma_f32_16x16x32_bf16 v[62:65], v[150:153], v[184:187], v[62:65]
	v_mfma_f32_16x16x32_bf16 v[58:61], v[142:145], v[192:195], v[58:61]
	v_mfma_f32_16x16x32_bf16 v[54:57], v[150:153], v[192:195], v[54:57]
	v_mfma_f32_16x16x32_bf16 v[50:53], v[142:145], v[200:203], v[50:53]
	v_mfma_f32_16x16x32_bf16 v[46:49], v[150:153], v[200:203], v[46:49]
	v_mfma_f32_16x16x32_bf16 v[42:45], v[142:145], v[210:213], v[42:45]
	v_mfma_f32_16x16x32_bf16 v[38:41], v[150:153], v[210:213], v[38:41]
	v_mfma_f32_16x16x32_bf16 v[66:69], v[146:149], v[188:191], v[66:69]
	v_mfma_f32_16x16x32_bf16 v[62:65], v[154:157], v[188:191], v[62:65]
	v_mfma_f32_16x16x32_bf16 v[58:61], v[146:149], v[196:199], v[58:61]
	v_mfma_f32_16x16x32_bf16 v[54:57], v[154:157], v[196:199], v[54:57]
	v_mfma_f32_16x16x32_bf16 v[50:53], v[146:149], v[204:207], v[50:53]
	v_mfma_f32_16x16x32_bf16 v[46:49], v[154:157], v[204:207], v[46:49]
	v_mfma_f32_16x16x32_bf16 v[42:45], v[146:149], v[214:217], v[42:45]
	v_mfma_f32_16x16x32_bf16 v[38:41], v[154:157], v[214:217], v[38:41]
	v_mfma_f32_16x16x32_bf16 v[34:37], v[158:161], v[184:187], v[34:37]
	v_mfma_f32_16x16x32_bf16 v[30:33], v[166:169], v[184:187], v[30:33]
	v_mfma_f32_16x16x32_bf16 v[26:29], v[158:161], v[192:195], v[26:29]
	v_mfma_f32_16x16x32_bf16 v[22:25], v[166:169], v[192:195], v[22:25]
	v_mfma_f32_16x16x32_bf16 v[18:21], v[158:161], v[200:203], v[18:21]
	v_mfma_f32_16x16x32_bf16 v[14:17], v[166:169], v[200:203], v[14:17]
	v_mfma_f32_16x16x32_bf16 v[10:13], v[158:161], v[210:213], v[10:13]
	v_mfma_f32_16x16x32_bf16 v[6:9], v[166:169], v[210:213], v[6:9]
	v_mfma_f32_16x16x32_bf16 v[34:37], v[162:165], v[188:191], v[34:37]
	v_mfma_f32_16x16x32_bf16 v[30:33], v[180:183], v[188:191], v[30:33]
	v_mfma_f32_16x16x32_bf16 v[26:29], v[162:165], v[196:199], v[26:29]
	v_mfma_f32_16x16x32_bf16 v[22:25], v[180:183], v[196:199], v[22:25]
	v_mfma_f32_16x16x32_bf16 v[18:21], v[162:165], v[204:207], v[18:21]
	v_mfma_f32_16x16x32_bf16 v[14:17], v[180:183], v[204:207], v[14:17]
	v_mfma_f32_16x16x32_bf16 v[10:13], v[162:165], v[214:217], v[10:13]
	v_mfma_f32_16x16x32_bf16 v[6:9], v[180:183], v[214:217], v[6:9]
	s_barrier
	s_add_i32 s16, 0, 0x18000
	v_add_u32_e32 v2, s16, v173
	s_add_i32 s17, 0, 0x1c000
	ds_read_b128 v[142:145], v2
	ds_read_b128 v[146:149], v2 offset:1024
	ds_read_b128 v[150:153], v2 offset:2048
	ds_read_b128 v[154:157], v2 offset:3072
	v_add_u32_e32 v2, s17, v173
	ds_read_b128 v[158:161], v2
	ds_read_b128 v[162:165], v2 offset:1024
	ds_read_b128 v[166:169], v2 offset:2048
	ds_read_b128 v[180:183], v2 offset:3072
	s_add_u32 s14, s14, s23
	s_addc_u32 s15, s15, s22
	s_mov_b32 m0, s57
	ds_read_b128 v[184:187], v176 offset:32768
	ds_read_b128 v[188:191], v176 offset:33792
	ds_read_b128 v[192:195], v176 offset:34816
	ds_read_b128 v[196:199], v176 offset:35840
	ds_read_b128 v[200:203], v176 offset:36864
	ds_read_b128 v[204:207], v176 offset:37888
	ds_read_b128 v[210:213], v176 offset:38912
	ds_read_b128 v[214:217], v176 offset:39936
	global_load_lds_dwordx4 v222, s[14:15]
	s_mov_b32 m0, s0
	s_nop 0
	global_load_lds_dwordx4 v230, s[14:15]
	s_waitcnt vmcnt(8)
	s_waitcnt lgkmcnt(0)
	s_barrier
	s_waitcnt lgkmcnt(0)
	v_mfma_f32_16x16x32_bf16 v[130:133], v[142:145], v[184:187], v[130:133]
	v_mfma_f32_16x16x32_bf16 v[126:129], v[150:153], v[184:187], v[126:129]
	v_mfma_f32_16x16x32_bf16 v[122:125], v[142:145], v[192:195], v[122:125]
	v_mfma_f32_16x16x32_bf16 v[118:121], v[150:153], v[192:195], v[118:121]
	v_mfma_f32_16x16x32_bf16 v[114:117], v[142:145], v[200:203], v[114:117]
	v_mfma_f32_16x16x32_bf16 v[110:113], v[150:153], v[200:203], v[110:113]
	v_mfma_f32_16x16x32_bf16 v[106:109], v[142:145], v[210:213], v[106:109]
	v_mfma_f32_16x16x32_bf16 v[102:105], v[150:153], v[210:213], v[102:105]
	v_mfma_f32_16x16x32_bf16 v[130:133], v[146:149], v[188:191], v[130:133]
	v_mfma_f32_16x16x32_bf16 v[126:129], v[154:157], v[188:191], v[126:129]
	v_mfma_f32_16x16x32_bf16 v[122:125], v[146:149], v[196:199], v[122:125]
	v_mfma_f32_16x16x32_bf16 v[118:121], v[154:157], v[196:199], v[118:121]
	v_mfma_f32_16x16x32_bf16 v[114:117], v[146:149], v[204:207], v[114:117]
	v_mfma_f32_16x16x32_bf16 v[110:113], v[154:157], v[204:207], v[110:113]
	v_mfma_f32_16x16x32_bf16 v[106:109], v[146:149], v[214:217], v[106:109]
	v_mfma_f32_16x16x32_bf16 v[102:105], v[154:157], v[214:217], v[102:105]
	v_mfma_f32_16x16x32_bf16 v[98:101], v[158:161], v[184:187], v[98:101]
	v_mfma_f32_16x16x32_bf16 v[94:97], v[166:169], v[184:187], v[94:97]
	v_mfma_f32_16x16x32_bf16 v[90:93], v[158:161], v[192:195], v[90:93]
	v_mfma_f32_16x16x32_bf16 v[86:89], v[166:169], v[192:195], v[86:89]
	v_mfma_f32_16x16x32_bf16 v[82:85], v[158:161], v[200:203], v[82:85]
	v_mfma_f32_16x16x32_bf16 v[78:81], v[166:169], v[200:203], v[78:81]
	v_mfma_f32_16x16x32_bf16 v[74:77], v[158:161], v[210:213], v[74:77]
	v_mfma_f32_16x16x32_bf16 v[70:73], v[166:169], v[210:213], v[70:73]
	v_mfma_f32_16x16x32_bf16 v[98:101], v[162:165], v[188:191], v[98:101]
	v_mfma_f32_16x16x32_bf16 v[94:97], v[180:183], v[188:191], v[94:97]
	v_mfma_f32_16x16x32_bf16 v[90:93], v[162:165], v[196:199], v[90:93]
	v_mfma_f32_16x16x32_bf16 v[86:89], v[180:183], v[196:199], v[86:89]
	v_mfma_f32_16x16x32_bf16 v[82:85], v[162:165], v[204:207], v[82:85]
	v_mfma_f32_16x16x32_bf16 v[78:81], v[180:183], v[204:207], v[78:81]
	v_mfma_f32_16x16x32_bf16 v[74:77], v[162:165], v[214:217], v[74:77]
	v_mfma_f32_16x16x32_bf16 v[70:73], v[180:183], v[214:217], v[70:73]
	s_barrier
	s_add_i32 s14, s16, s5
	v_lshl_add_u64 v[220:221], v[220:221], 0, s[90:91]
	s_mov_b32 m0, s14
	ds_read_b128 v[184:187], v176 offset:49152
	ds_read_b128 v[188:191], v176 offset:50176
	ds_read_b128 v[192:195], v176 offset:51200
	ds_read_b128 v[196:199], v176 offset:52224
	ds_read_b128 v[200:203], v176 offset:53248
	ds_read_b128 v[204:207], v176 offset:54272
	ds_read_b128 v[210:213], v176 offset:55296
	ds_read_b128 v[214:217], v176 offset:56320
	global_load_lds_dwordx4 v[220:221], off
	v_lshl_add_u64 v[220:221], v[224:225], 0, s[90:91]
	s_add_i32 m0, s14, 0x2000
	s_add_i32 s14, s17, s5
	global_load_lds_dwordx4 v[220:221], off
	v_lshl_add_u64 v[220:221], v[226:227], 0, s[90:91]
	s_mov_b32 m0, s14
	v_lshl_add_u64 v[218:219], v[218:219], 0, s[90:91]
	global_load_lds_dwordx4 v[220:221], off
	s_add_i32 m0, s14, 0x2000
	s_nop 0
	global_load_lds_dwordx4 v[218:219], off
	v_lshl_add_u64 v[218:219], v[228:229], 0, s[90:91]
	s_mov_b32 m0, s43
	s_nop 0
	global_load_lds_dwordx4 v[218:219], off
	v_lshl_add_u64 v[218:219], v[232:233], 0, s[90:91]
	s_mov_b32 m0, s76
	s_nop 0
	global_load_lds_dwordx4 v[218:219], off
	s_waitcnt vmcnt(8)
	s_waitcnt lgkmcnt(0)
	s_barrier
	s_waitcnt lgkmcnt(0)
	v_mfma_f32_16x16x32_bf16 v[66:69], v[142:145], v[184:187], v[66:69]
	v_mfma_f32_16x16x32_bf16 v[62:65], v[150:153], v[184:187], v[62:65]
	v_mfma_f32_16x16x32_bf16 v[58:61], v[142:145], v[192:195], v[58:61]
	v_mfma_f32_16x16x32_bf16 v[54:57], v[150:153], v[192:195], v[54:57]
	v_mfma_f32_16x16x32_bf16 v[50:53], v[142:145], v[200:203], v[50:53]
	v_mfma_f32_16x16x32_bf16 v[46:49], v[150:153], v[200:203], v[46:49]
	v_mfma_f32_16x16x32_bf16 v[42:45], v[142:145], v[210:213], v[42:45]
	v_mfma_f32_16x16x32_bf16 v[38:41], v[150:153], v[210:213], v[38:41]
	v_mfma_f32_16x16x32_bf16 v[66:69], v[146:149], v[188:191], v[66:69]
	v_mfma_f32_16x16x32_bf16 v[62:65], v[154:157], v[188:191], v[62:65]
	v_mfma_f32_16x16x32_bf16 v[58:61], v[146:149], v[196:199], v[58:61]
	v_mfma_f32_16x16x32_bf16 v[54:57], v[154:157], v[196:199], v[54:57]
	v_mfma_f32_16x16x32_bf16 v[50:53], v[146:149], v[204:207], v[50:53]
	v_mfma_f32_16x16x32_bf16 v[46:49], v[154:157], v[204:207], v[46:49]
	v_mfma_f32_16x16x32_bf16 v[42:45], v[146:149], v[214:217], v[42:45]
	v_mfma_f32_16x16x32_bf16 v[38:41], v[154:157], v[214:217], v[38:41]
	v_mfma_f32_16x16x32_bf16 v[34:37], v[158:161], v[184:187], v[34:37]
	v_mfma_f32_16x16x32_bf16 v[30:33], v[166:169], v[184:187], v[30:33]
	v_mfma_f32_16x16x32_bf16 v[26:29], v[158:161], v[192:195], v[26:29]
	v_mfma_f32_16x16x32_bf16 v[22:25], v[166:169], v[192:195], v[22:25]
	v_mfma_f32_16x16x32_bf16 v[18:21], v[158:161], v[200:203], v[18:21]
	v_mfma_f32_16x16x32_bf16 v[14:17], v[166:169], v[200:203], v[14:17]
	v_mfma_f32_16x16x32_bf16 v[10:13], v[158:161], v[210:213], v[10:13]
	v_mfma_f32_16x16x32_bf16 v[6:9], v[166:169], v[210:213], v[6:9]
	v_mfma_f32_16x16x32_bf16 v[34:37], v[162:165], v[188:191], v[34:37]
	v_mfma_f32_16x16x32_bf16 v[30:33], v[180:183], v[188:191], v[30:33]
	v_mfma_f32_16x16x32_bf16 v[26:29], v[162:165], v[196:199], v[26:29]
	v_mfma_f32_16x16x32_bf16 v[22:25], v[180:183], v[196:199], v[22:25]
	v_mfma_f32_16x16x32_bf16 v[18:21], v[162:165], v[204:207], v[18:21]
	v_mfma_f32_16x16x32_bf16 v[14:17], v[180:183], v[204:207], v[14:17]
	v_mfma_f32_16x16x32_bf16 v[10:13], v[162:165], v[214:217], v[10:13]
	v_mfma_f32_16x16x32_bf16 v[6:9], v[180:183], v[214:217], v[6:9]
	s_barrier
	s_add_u32 s19, s19, 0x100
	s_addc_u32 s20, s20, 0
	s_add_u32 s12, s12, 0x100
	s_addc_u32 s13, s13, 0
	s_cmp_ge_i32 s21, s27
	s_mov_b32 s14, s21
	s_cbranch_scc0 .LBB0_341

.LBB0_626:
	ds_read_b128 v[130:133], v170
	ds_read_b128 v[150:153], v170 offset:1024
	ds_read_b128 v[154:157], v170 offset:2048
	ds_read_b128 v[158:161], v170 offset:3072
	ds_read_b128 v[162:165], v171
	ds_read_b128 v[174:177], v171 offset:1024
	ds_read_b128 v[178:181], v171 offset:2048
	ds_read_b128 v[182:185], v171 offset:3072
	s_add_i32 s46, s44, 2
	s_add_u32 s47, s0, 0x80
	s_addc_u32 s45, s1, 0
	s_cmp_eq_u32 s80, s44
	s_cselect_b32 s44, s40, s47
	s_cselect_b32 s45, s41, s45
	s_cselect_b32 vcc_hi, s43, s96
	s_cselect_b32 vcc_lo, s42, s95
	v_lshl_add_u64 v[166:167], s[0:1], 0, v[146:147]
	s_add_i32 m0, s56, 0xc000
	ds_read_b128 v[186:189], v172
	ds_read_b128 v[190:193], v172 offset:1024
	ds_read_b128 v[194:197], v172 offset:2048
	ds_read_b128 v[198:201], v172 offset:3072
	ds_read_b128 v[202:205], v172 offset:4096
	ds_read_b128 v[210:213], v172 offset:5120
	ds_read_b128 v[214:217], v172 offset:6144
	ds_read_b128 v[218:221], v172 offset:7168
	global_load_lds_dwordx4 v[166:167], off
	v_lshl_add_u64 v[166:167], s[0:1], 0, v[144:145]
	s_add_i32 m0, s56, 0xe000
	s_nop 0
	global_load_lds_dwordx4 v[166:167], off
	s_waitcnt vmcnt(8)
	s_waitcnt lgkmcnt(0)
	s_barrier
	s_waitcnt lgkmcnt(0)
	v_mfma_f32_16x16x32_bf16 v[122:125], v[130:133], v[186:189], v[122:125]
	v_mfma_f32_16x16x32_bf16 v[126:129], v[154:157], v[186:189], v[126:129]
	v_mfma_f32_16x16x32_bf16 v[110:113], v[130:133], v[194:197], v[110:113]
	v_mfma_f32_16x16x32_bf16 v[106:109], v[154:157], v[194:197], v[106:109]
	v_mfma_f32_16x16x32_bf16 v[94:97], v[130:133], v[202:205], v[94:97]
	v_mfma_f32_16x16x32_bf16 v[90:93], v[154:157], v[202:205], v[90:93]
	v_mfma_f32_16x16x32_bf16 v[78:81], v[130:133], v[214:217], v[78:81]
	v_mfma_f32_16x16x32_bf16 v[74:77], v[154:157], v[214:217], v[74:77]
	v_mfma_f32_16x16x32_bf16 v[122:125], v[150:153], v[190:193], v[122:125]
	v_mfma_f32_16x16x32_bf16 v[126:129], v[158:161], v[190:193], v[126:129]
	v_mfma_f32_16x16x32_bf16 v[110:113], v[150:153], v[198:201], v[110:113]
	v_mfma_f32_16x16x32_bf16 v[106:109], v[158:161], v[198:201], v[106:109]
	v_mfma_f32_16x16x32_bf16 v[94:97], v[150:153], v[210:213], v[94:97]
	v_mfma_f32_16x16x32_bf16 v[90:93], v[158:161], v[210:213], v[90:93]
	v_mfma_f32_16x16x32_bf16 v[78:81], v[150:153], v[218:221], v[78:81]
	v_mfma_f32_16x16x32_bf16 v[74:77], v[158:161], v[218:221], v[74:77]
	v_mfma_f32_16x16x32_bf16 v[118:121], v[162:165], v[186:189], v[118:121]
	v_mfma_f32_16x16x32_bf16 v[114:117], v[178:181], v[186:189], v[114:117]
	v_mfma_f32_16x16x32_bf16 v[102:105], v[162:165], v[194:197], v[102:105]
	v_mfma_f32_16x16x32_bf16 v[98:101], v[178:181], v[194:197], v[98:101]
	v_mfma_f32_16x16x32_bf16 v[86:89], v[162:165], v[202:205], v[86:89]
	v_mfma_f32_16x16x32_bf16 v[82:85], v[178:181], v[202:205], v[82:85]
	v_mfma_f32_16x16x32_bf16 v[70:73], v[162:165], v[214:217], v[70:73]
	v_mfma_f32_16x16x32_bf16 v[66:69], v[178:181], v[214:217], v[66:69]
	v_mfma_f32_16x16x32_bf16 v[118:121], v[174:177], v[190:193], v[118:121]
	v_mfma_f32_16x16x32_bf16 v[114:117], v[182:185], v[190:193], v[114:117]
	v_mfma_f32_16x16x32_bf16 v[102:105], v[174:177], v[198:201], v[102:105]
	v_mfma_f32_16x16x32_bf16 v[98:101], v[182:185], v[198:201], v[98:101]
	v_mfma_f32_16x16x32_bf16 v[86:89], v[174:177], v[210:213], v[86:89]
	v_mfma_f32_16x16x32_bf16 v[82:85], v[182:185], v[210:213], v[82:85]
	v_mfma_f32_16x16x32_bf16 v[70:73], v[174:177], v[218:221], v[70:73]
	v_mfma_f32_16x16x32_bf16 v[66:69], v[182:185], v[218:221], v[66:69]
	s_barrier
	s_add_i32 s47, s86, s55
	v_lshl_add_u64 v[166:167], vcc, 0, v[136:137]
	s_mov_b32 m0, s47
	ds_read_b128 v[186:189], v172 offset:16384
	ds_read_b128 v[190:193], v172 offset:17408
	ds_read_b128 v[194:197], v172 offset:18432
	ds_read_b128 v[198:201], v172 offset:19456
	ds_read_b128 v[202:205], v172 offset:20480
	ds_read_b128 v[210:213], v172 offset:21504
	ds_read_b128 v[214:217], v172 offset:22528
	ds_read_b128 v[218:221], v172 offset:23552
	global_load_lds_dwordx4 v[166:167], off
	s_add_i32 m0, s47, 0x2000
	v_lshl_add_u64 v[206:207], vcc, 0, v[138:139]
	s_add_u32 vcc_lo, vcc_lo, s16
	s_addc_u32 vcc_hi, vcc_hi, s17
	s_add_i32 s47, s87, s55
	global_load_lds_dwordx4 v[206:207], off
	v_lshl_add_u64 v[222:223], vcc, 0, v[136:137]
	s_mov_b32 m0, s47
	v_lshl_add_u64 v[224:225], vcc, 0, v[138:139]
	global_load_lds_dwordx4 v[222:223], off
	s_add_i32 m0, s47, 0x2000
	v_lshl_add_u64 v[226:227], s[44:45], 0, v[140:141]
	global_load_lds_dwordx4 v[224:225], off
	s_mov_b32 m0, s56
	v_lshl_add_u64 v[228:229], s[44:45], 0, v[142:143]
	global_load_lds_dwordx4 v[226:227], off
	s_mov_b32 m0, s57
	s_nop 0
	global_load_lds_dwordx4 v[228:229], off
	s_waitcnt vmcnt(8)
	s_waitcnt lgkmcnt(0)
	s_barrier
	s_waitcnt lgkmcnt(0)
	v_mfma_f32_16x16x32_bf16 v[62:65], v[130:133], v[186:189], v[62:65]
	v_mfma_f32_16x16x32_bf16 v[58:61], v[154:157], v[186:189], v[58:61]
	v_mfma_f32_16x16x32_bf16 v[46:49], v[130:133], v[194:197], v[46:49]
	v_mfma_f32_16x16x32_bf16 v[42:45], v[154:157], v[194:197], v[42:45]
	v_mfma_f32_16x16x32_bf16 v[30:33], v[130:133], v[202:205], v[30:33]
	v_mfma_f32_16x16x32_bf16 v[26:29], v[154:157], v[202:205], v[26:29]
	v_mfma_f32_16x16x32_bf16 v[14:17], v[130:133], v[214:217], v[14:17]
	v_mfma_f32_16x16x32_bf16 v[10:13], v[154:157], v[214:217], v[10:13]
	v_mfma_f32_16x16x32_bf16 v[62:65], v[150:153], v[190:193], v[62:65]
	v_mfma_f32_16x16x32_bf16 v[58:61], v[158:161], v[190:193], v[58:61]
	v_mfma_f32_16x16x32_bf16 v[46:49], v[150:153], v[198:201], v[46:49]
	v_mfma_f32_16x16x32_bf16 v[42:45], v[158:161], v[198:201], v[42:45]
	v_mfma_f32_16x16x32_bf16 v[30:33], v[150:153], v[210:213], v[30:33]
	v_mfma_f32_16x16x32_bf16 v[26:29], v[158:161], v[210:213], v[26:29]
	v_mfma_f32_16x16x32_bf16 v[14:17], v[150:153], v[218:221], v[14:17]
	v_mfma_f32_16x16x32_bf16 v[10:13], v[158:161], v[218:221], v[10:13]
	v_mfma_f32_16x16x32_bf16 v[54:57], v[162:165], v[186:189], v[54:57]
	v_mfma_f32_16x16x32_bf16 v[50:53], v[178:181], v[186:189], v[50:53]
	v_mfma_f32_16x16x32_bf16 v[38:41], v[162:165], v[194:197], v[38:41]
	v_mfma_f32_16x16x32_bf16 v[34:37], v[178:181], v[194:197], v[34:37]
	v_mfma_f32_16x16x32_bf16 v[22:25], v[162:165], v[202:205], v[22:25]
	v_mfma_f32_16x16x32_bf16 v[18:21], v[178:181], v[202:205], v[18:21]
	v_mfma_f32_16x16x32_bf16 v[6:9], v[162:165], v[214:217], v[6:9]
	v_mfma_f32_16x16x32_bf16 v[2:5], v[178:181], v[214:217], v[2:5]
	v_mfma_f32_16x16x32_bf16 v[54:57], v[174:177], v[190:193], v[54:57]
	v_mfma_f32_16x16x32_bf16 v[50:53], v[182:185], v[190:193], v[50:53]
	v_mfma_f32_16x16x32_bf16 v[38:41], v[174:177], v[198:201], v[38:41]
	v_mfma_f32_16x16x32_bf16 v[34:37], v[182:185], v[198:201], v[34:37]
	v_mfma_f32_16x16x32_bf16 v[22:25], v[174:177], v[210:213], v[22:25]
	v_mfma_f32_16x16x32_bf16 v[18:21], v[182:185], v[210:213], v[18:21]
	v_mfma_f32_16x16x32_bf16 v[6:9], v[174:177], v[218:221], v[6:9]
	v_mfma_f32_16x16x32_bf16 v[2:5], v[182:185], v[218:221], v[2:5]
	s_barrier
	s_add_i32 s47, 0, 0x18000
	s_add_i32 vcc_lo, 0, 0x1c000
	v_add_u32_e32 v158, s47, v169
	v_add_u32_e32 v182, vcc_lo, v169
	ds_read_b128 v[130:133], v158
	ds_read_b128 v[150:153], v158 offset:1024
	ds_read_b128 v[154:157], v158 offset:2048
	ds_read_b128 v[158:161], v158 offset:3072
	ds_read_b128 v[162:165], v182
	ds_read_b128 v[174:177], v182 offset:1024
	ds_read_b128 v[178:181], v182 offset:2048
	ds_read_b128 v[182:185], v182 offset:3072
	s_add_u32 s44, s44, s16
	s_addc_u32 s45, s45, s17
	s_mov_b32 m0, s58
	v_lshl_add_u64 v[230:231], s[44:45], 0, v[140:141]
	ds_read_b128 v[186:189], v172 offset:32768
	ds_read_b128 v[190:193], v172 offset:33792
	ds_read_b128 v[194:197], v172 offset:34816
	ds_read_b128 v[198:201], v172 offset:35840
	ds_read_b128 v[202:205], v172 offset:36864
	ds_read_b128 v[210:213], v172 offset:37888
	ds_read_b128 v[214:217], v172 offset:38912
	ds_read_b128 v[218:221], v172 offset:39936
	global_load_lds_dwordx4 v[230:231], off
	v_lshl_add_u64 v[230:231], s[44:45], 0, v[142:143]
	s_mov_b32 m0, s59
	s_nop 0
	global_load_lds_dwordx4 v[230:231], off
	s_waitcnt vmcnt(8)
	s_waitcnt lgkmcnt(0)
	s_barrier
	s_waitcnt lgkmcnt(0)
	v_mfma_f32_16x16x32_bf16 v[122:125], v[130:133], v[186:189], v[122:125]
	v_mfma_f32_16x16x32_bf16 v[126:129], v[154:157], v[186:189], v[126:129]
	v_mfma_f32_16x16x32_bf16 v[110:113], v[130:133], v[194:197], v[110:113]
	v_mfma_f32_16x16x32_bf16 v[106:109], v[154:157], v[194:197], v[106:109]
	v_mfma_f32_16x16x32_bf16 v[94:97], v[130:133], v[202:205], v[94:97]
	v_mfma_f32_16x16x32_bf16 v[90:93], v[154:157], v[202:205], v[90:93]
	v_mfma_f32_16x16x32_bf16 v[78:81], v[130:133], v[214:217], v[78:81]
	v_mfma_f32_16x16x32_bf16 v[74:77], v[154:157], v[214:217], v[74:77]
	v_mfma_f32_16x16x32_bf16 v[122:125], v[150:153], v[190:193], v[122:125]
	v_mfma_f32_16x16x32_bf16 v[126:129], v[158:161], v[190:193], v[126:129]
	v_mfma_f32_16x16x32_bf16 v[110:113], v[150:153], v[198:201], v[110:113]
	v_mfma_f32_16x16x32_bf16 v[106:109], v[158:161], v[198:201], v[106:109]
	v_mfma_f32_16x16x32_bf16 v[94:97], v[150:153], v[210:213], v[94:97]
	v_mfma_f32_16x16x32_bf16 v[90:93], v[158:161], v[210:213], v[90:93]
	v_mfma_f32_16x16x32_bf16 v[78:81], v[150:153], v[218:221], v[78:81]
	v_mfma_f32_16x16x32_bf16 v[74:77], v[158:161], v[218:221], v[74:77]
	v_mfma_f32_16x16x32_bf16 v[118:121], v[162:165], v[186:189], v[118:121]
	v_mfma_f32_16x16x32_bf16 v[114:117], v[178:181], v[186:189], v[114:117]
	v_mfma_f32_16x16x32_bf16 v[102:105], v[162:165], v[194:197], v[102:105]
	v_mfma_f32_16x16x32_bf16 v[98:101], v[178:181], v[194:197], v[98:101]
	v_mfma_f32_16x16x32_bf16 v[86:89], v[162:165], v[202:205], v[86:89]
	v_mfma_f32_16x16x32_bf16 v[82:85], v[178:181], v[202:205], v[82:85]
	v_mfma_f32_16x16x32_bf16 v[70:73], v[162:165], v[214:217], v[70:73]
	v_mfma_f32_16x16x32_bf16 v[66:69], v[178:181], v[214:217], v[66:69]
	v_mfma_f32_16x16x32_bf16 v[118:121], v[174:177], v[190:193], v[118:121]
	v_mfma_f32_16x16x32_bf16 v[114:117], v[182:185], v[190:193], v[114:117]
	v_mfma_f32_16x16x32_bf16 v[102:105], v[174:177], v[198:201], v[102:105]
	v_mfma_f32_16x16x32_bf16 v[98:101], v[182:185], v[198:201], v[98:101]
	v_mfma_f32_16x16x32_bf16 v[86:89], v[174:177], v[210:213], v[86:89]
	v_mfma_f32_16x16x32_bf16 v[82:85], v[182:185], v[210:213], v[82:85]
	v_mfma_f32_16x16x32_bf16 v[70:73], v[174:177], v[218:221], v[70:73]
	v_mfma_f32_16x16x32_bf16 v[66:69], v[182:185], v[218:221], v[66:69]
	s_barrier
	s_add_i32 s44, s47, s55
	v_lshl_add_u64 v[166:167], v[166:167], 0, s[24:25]
	s_mov_b32 m0, s44
	ds_read_b128 v[186:189], v172 offset:49152
	ds_read_b128 v[190:193], v172 offset:50176
	ds_read_b128 v[194:197], v172 offset:51200
	ds_read_b128 v[198:201], v172 offset:52224
	ds_read_b128 v[202:205], v172 offset:53248
	ds_read_b128 v[210:213], v172 offset:54272
	ds_read_b128 v[214:217], v172 offset:55296
	ds_read_b128 v[218:221], v172 offset:56320
	global_load_lds_dwordx4 v[166:167], off
	v_lshl_add_u64 v[166:167], v[206:207], 0, s[24:25]
	s_add_i32 m0, s44, 0x2000
	s_add_i32 s44, vcc_lo, s55
	global_load_lds_dwordx4 v[166:167], off
	v_lshl_add_u64 v[166:167], v[222:223], 0, s[24:25]
	s_mov_b32 m0, s44
	s_nop 0
	global_load_lds_dwordx4 v[166:167], off
	v_lshl_add_u64 v[166:167], v[224:225], 0, s[24:25]
	s_add_i32 m0, s44, 0x2000
	s_nop 0
	global_load_lds_dwordx4 v[166:167], off
	v_lshl_add_u64 v[166:167], v[226:227], 0, s[24:25]
	s_mov_b32 m0, s63
	s_nop 0
	global_load_lds_dwordx4 v[166:167], off
	v_lshl_add_u64 v[166:167], v[228:229], 0, s[24:25]
	s_mov_b32 m0, s64
	s_nop 0
	global_load_lds_dwordx4 v[166:167], off
	s_waitcnt vmcnt(8)
	s_waitcnt lgkmcnt(0)
	s_barrier
	s_waitcnt lgkmcnt(0)
	v_mfma_f32_16x16x32_bf16 v[62:65], v[130:133], v[186:189], v[62:65]
	v_mfma_f32_16x16x32_bf16 v[58:61], v[154:157], v[186:189], v[58:61]
	v_mfma_f32_16x16x32_bf16 v[46:49], v[130:133], v[194:197], v[46:49]
	v_mfma_f32_16x16x32_bf16 v[42:45], v[154:157], v[194:197], v[42:45]
	v_mfma_f32_16x16x32_bf16 v[30:33], v[130:133], v[202:205], v[30:33]
	v_mfma_f32_16x16x32_bf16 v[26:29], v[154:157], v[202:205], v[26:29]
	v_mfma_f32_16x16x32_bf16 v[14:17], v[130:133], v[214:217], v[14:17]
	v_mfma_f32_16x16x32_bf16 v[10:13], v[154:157], v[214:217], v[10:13]
	v_mfma_f32_16x16x32_bf16 v[62:65], v[150:153], v[190:193], v[62:65]
	v_mfma_f32_16x16x32_bf16 v[58:61], v[158:161], v[190:193], v[58:61]
	v_mfma_f32_16x16x32_bf16 v[46:49], v[150:153], v[198:201], v[46:49]
	v_mfma_f32_16x16x32_bf16 v[42:45], v[158:161], v[198:201], v[42:45]
	v_mfma_f32_16x16x32_bf16 v[30:33], v[150:153], v[210:213], v[30:33]
	v_mfma_f32_16x16x32_bf16 v[26:29], v[158:161], v[210:213], v[26:29]
	v_mfma_f32_16x16x32_bf16 v[14:17], v[150:153], v[218:221], v[14:17]
	v_mfma_f32_16x16x32_bf16 v[10:13], v[158:161], v[218:221], v[10:13]
	v_mfma_f32_16x16x32_bf16 v[54:57], v[162:165], v[186:189], v[54:57]
	v_mfma_f32_16x16x32_bf16 v[50:53], v[178:181], v[186:189], v[50:53]
	v_mfma_f32_16x16x32_bf16 v[38:41], v[162:165], v[194:197], v[38:41]
	v_mfma_f32_16x16x32_bf16 v[34:37], v[178:181], v[194:197], v[34:37]
	v_mfma_f32_16x16x32_bf16 v[22:25], v[162:165], v[202:205], v[22:25]
	v_mfma_f32_16x16x32_bf16 v[18:21], v[178:181], v[202:205], v[18:21]
	v_mfma_f32_16x16x32_bf16 v[6:9], v[162:165], v[214:217], v[6:9]
	v_mfma_f32_16x16x32_bf16 v[2:5], v[178:181], v[214:217], v[2:5]
	v_mfma_f32_16x16x32_bf16 v[54:57], v[174:177], v[190:193], v[54:57]
	v_mfma_f32_16x16x32_bf16 v[50:53], v[182:185], v[190:193], v[50:53]
	v_mfma_f32_16x16x32_bf16 v[38:41], v[174:177], v[198:201], v[38:41]
	v_mfma_f32_16x16x32_bf16 v[34:37], v[182:185], v[198:201], v[34:37]
	v_mfma_f32_16x16x32_bf16 v[22:25], v[174:177], v[210:213], v[22:25]
	v_mfma_f32_16x16x32_bf16 v[18:21], v[182:185], v[210:213], v[18:21]
	v_mfma_f32_16x16x32_bf16 v[6:9], v[174:177], v[218:221], v[6:9]
	v_mfma_f32_16x16x32_bf16 v[2:5], v[182:185], v[218:221], v[2:5]
	s_barrier
	s_add_u32 s95, s95, 0x100
	s_addc_u32 s96, s96, 0
	s_add_u32 s0, s0, 0x100
	s_addc_u32 s1, s1, 0
	s_cmp_ge_i32 s46, s65
	s_mov_b32 s44, s46
	s_cbranch_scc0 .LBB0_626

.LBB0_1087:
	v_add_u32_e32 v149, s71, v146
	ds_read_b128 v[142:145], v149
	ds_read_b128 v[152:155], v149 offset:1024
	ds_read_b128 v[156:159], v149 offset:2048
	ds_read_b128 v[160:163], v149 offset:3072
	v_add_u32_e32 v149, s72, v146
	ds_read_b128 v[164:167], v149
	ds_read_b128 v[168:171], v149 offset:1024
	ds_read_b128 v[172:175], v149 offset:2048
	ds_read_b128 v[176:179], v149 offset:3072
	s_add_i32 s42, s40, 2
	s_add_u32 s43, s4, 0x80
	s_addc_u32 s41, s5, 0
	s_cmp_eq_u32 s58, s40
	s_cselect_b32 s40, s36, s43
	s_cselect_b32 s41, s37, s41
	s_cselect_b32 s81, s39, s78
	s_cselect_b32 s80, s38, s77
	v_lshl_add_u64 v[214:215], s[4:5], 0, v[140:141]
	s_add_i32 m0, s48, 0xc000
	ds_read_b128 v[180:183], v147
	ds_read_b128 v[184:187], v147 offset:1024
	ds_read_b128 v[188:191], v147 offset:2048
	ds_read_b128 v[192:195], v147 offset:3072
	ds_read_b128 v[196:199], v147 offset:4096
	ds_read_b128 v[200:203], v147 offset:5120
	ds_read_b128 v[204:207], v147 offset:6144
	ds_read_b128 v[210:213], v147 offset:7168
	global_load_lds_dwordx4 v[214:215], off
	v_lshl_add_u64 v[214:215], s[4:5], 0, v[138:139]
	s_add_i32 m0, s48, 0xe000
	s_nop 0
	global_load_lds_dwordx4 v[214:215], off
	s_waitcnt vmcnt(8)
	s_waitcnt lgkmcnt(0)
	s_barrier
	s_waitcnt lgkmcnt(0)
	v_mfma_f32_16x16x32_bf16 v[126:129], v[142:145], v[180:183], v[126:129]
	v_mfma_f32_16x16x32_bf16 v[122:125], v[156:159], v[180:183], v[122:125]
	v_mfma_f32_16x16x32_bf16 v[110:113], v[142:145], v[188:191], v[110:113]
	v_mfma_f32_16x16x32_bf16 v[106:109], v[156:159], v[188:191], v[106:109]
	v_mfma_f32_16x16x32_bf16 v[94:97], v[142:145], v[196:199], v[94:97]
	v_mfma_f32_16x16x32_bf16 v[90:93], v[156:159], v[196:199], v[90:93]
	v_mfma_f32_16x16x32_bf16 v[78:81], v[142:145], v[204:207], v[78:81]
	v_mfma_f32_16x16x32_bf16 v[74:77], v[156:159], v[204:207], v[74:77]
	v_mfma_f32_16x16x32_bf16 v[126:129], v[152:155], v[184:187], v[126:129]
	v_mfma_f32_16x16x32_bf16 v[122:125], v[160:163], v[184:187], v[122:125]
	v_mfma_f32_16x16x32_bf16 v[110:113], v[152:155], v[192:195], v[110:113]
	v_mfma_f32_16x16x32_bf16 v[106:109], v[160:163], v[192:195], v[106:109]
	v_mfma_f32_16x16x32_bf16 v[94:97], v[152:155], v[200:203], v[94:97]
	v_mfma_f32_16x16x32_bf16 v[90:93], v[160:163], v[200:203], v[90:93]
	v_mfma_f32_16x16x32_bf16 v[78:81], v[152:155], v[210:213], v[78:81]
	v_mfma_f32_16x16x32_bf16 v[74:77], v[160:163], v[210:213], v[74:77]
	v_mfma_f32_16x16x32_bf16 v[118:121], v[164:167], v[180:183], v[118:121]
	v_mfma_f32_16x16x32_bf16 v[114:117], v[172:175], v[180:183], v[114:117]
	v_mfma_f32_16x16x32_bf16 v[102:105], v[164:167], v[188:191], v[102:105]
	v_mfma_f32_16x16x32_bf16 v[98:101], v[172:175], v[188:191], v[98:101]
	v_mfma_f32_16x16x32_bf16 v[86:89], v[164:167], v[196:199], v[86:89]
	v_mfma_f32_16x16x32_bf16 v[82:85], v[172:175], v[196:199], v[82:85]
	v_mfma_f32_16x16x32_bf16 v[70:73], v[164:167], v[204:207], v[70:73]
	v_mfma_f32_16x16x32_bf16 v[66:69], v[172:175], v[204:207], v[66:69]
	v_mfma_f32_16x16x32_bf16 v[118:121], v[168:171], v[184:187], v[118:121]
	v_mfma_f32_16x16x32_bf16 v[114:117], v[176:179], v[184:187], v[114:117]
	v_mfma_f32_16x16x32_bf16 v[102:105], v[168:171], v[192:195], v[102:105]
	v_mfma_f32_16x16x32_bf16 v[98:101], v[176:179], v[192:195], v[98:101]
	v_mfma_f32_16x16x32_bf16 v[86:89], v[168:171], v[200:203], v[86:89]
	v_mfma_f32_16x16x32_bf16 v[82:85], v[176:179], v[200:203], v[82:85]
	v_mfma_f32_16x16x32_bf16 v[70:73], v[168:171], v[210:213], v[70:73]
	v_mfma_f32_16x16x32_bf16 v[66:69], v[176:179], v[210:213], v[66:69]
	s_barrier
	s_add_i32 s43, s71, s45
	v_lshl_add_u64 v[214:215], s[80:81], 0, v[130:131]
	s_mov_b32 m0, s43
	ds_read_b128 v[180:183], v147 offset:16384
	ds_read_b128 v[184:187], v147 offset:17408
	ds_read_b128 v[188:191], v147 offset:18432
	ds_read_b128 v[192:195], v147 offset:19456
	ds_read_b128 v[196:199], v147 offset:20480
	ds_read_b128 v[200:203], v147 offset:21504
	ds_read_b128 v[204:207], v147 offset:22528
	ds_read_b128 v[210:213], v147 offset:23552
	global_load_lds_dwordx4 v[214:215], off
	s_add_i32 m0, s43, 0x2000
	v_lshl_add_u64 v[216:217], s[80:81], 0, v[132:133]
	s_add_u32 s80, s80, s12
	s_addc_u32 s81, s81, s13
	s_add_i32 s43, s72, s45
	global_load_lds_dwordx4 v[216:217], off
	v_lshl_add_u64 v[218:219], s[80:81], 0, v[130:131]
	s_mov_b32 m0, s43
	v_lshl_add_u64 v[220:221], s[80:81], 0, v[132:133]
	global_load_lds_dwordx4 v[218:219], off
	s_add_i32 m0, s43, 0x2000
	v_lshl_add_u64 v[222:223], s[40:41], 0, v[134:135]
	global_load_lds_dwordx4 v[220:221], off
	s_mov_b32 m0, s48
	v_lshl_add_u64 v[224:225], s[40:41], 0, v[136:137]
	global_load_lds_dwordx4 v[222:223], off
	s_mov_b32 m0, s49
	s_nop 0
	global_load_lds_dwordx4 v[224:225], off
	s_waitcnt vmcnt(8)
	s_waitcnt lgkmcnt(0)
	s_barrier
	s_waitcnt lgkmcnt(0)
	v_mfma_f32_16x16x32_bf16 v[62:65], v[142:145], v[180:183], v[62:65]
	v_mfma_f32_16x16x32_bf16 v[58:61], v[156:159], v[180:183], v[58:61]
	v_mfma_f32_16x16x32_bf16 v[46:49], v[142:145], v[188:191], v[46:49]
	v_mfma_f32_16x16x32_bf16 v[42:45], v[156:159], v[188:191], v[42:45]
	v_mfma_f32_16x16x32_bf16 v[30:33], v[142:145], v[196:199], v[30:33]
	v_mfma_f32_16x16x32_bf16 v[26:29], v[156:159], v[196:199], v[26:29]
	v_mfma_f32_16x16x32_bf16 v[14:17], v[142:145], v[204:207], v[14:17]
	v_mfma_f32_16x16x32_bf16 v[10:13], v[156:159], v[204:207], v[10:13]
	v_mfma_f32_16x16x32_bf16 v[62:65], v[152:155], v[184:187], v[62:65]
	v_mfma_f32_16x16x32_bf16 v[58:61], v[160:163], v[184:187], v[58:61]
	v_mfma_f32_16x16x32_bf16 v[46:49], v[152:155], v[192:195], v[46:49]
	v_mfma_f32_16x16x32_bf16 v[42:45], v[160:163], v[192:195], v[42:45]
	v_mfma_f32_16x16x32_bf16 v[30:33], v[152:155], v[200:203], v[30:33]
	v_mfma_f32_16x16x32_bf16 v[26:29], v[160:163], v[200:203], v[26:29]
	v_mfma_f32_16x16x32_bf16 v[14:17], v[152:155], v[210:213], v[14:17]
	v_mfma_f32_16x16x32_bf16 v[10:13], v[160:163], v[210:213], v[10:13]
	v_mfma_f32_16x16x32_bf16 v[54:57], v[164:167], v[180:183], v[54:57]
	v_mfma_f32_16x16x32_bf16 v[50:53], v[172:175], v[180:183], v[50:53]
	v_mfma_f32_16x16x32_bf16 v[38:41], v[164:167], v[188:191], v[38:41]
	v_mfma_f32_16x16x32_bf16 v[34:37], v[172:175], v[188:191], v[34:37]
	v_mfma_f32_16x16x32_bf16 v[22:25], v[164:167], v[196:199], v[22:25]
	v_mfma_f32_16x16x32_bf16 v[18:21], v[172:175], v[196:199], v[18:21]
	v_mfma_f32_16x16x32_bf16 v[6:9], v[164:167], v[204:207], v[6:9]
	v_mfma_f32_16x16x32_bf16 v[2:5], v[172:175], v[204:207], v[2:5]
	v_mfma_f32_16x16x32_bf16 v[54:57], v[168:171], v[184:187], v[54:57]
	v_mfma_f32_16x16x32_bf16 v[50:53], v[176:179], v[184:187], v[50:53]
	v_mfma_f32_16x16x32_bf16 v[38:41], v[168:171], v[192:195], v[38:41]
	v_mfma_f32_16x16x32_bf16 v[34:37], v[176:179], v[192:195], v[34:37]
	v_mfma_f32_16x16x32_bf16 v[22:25], v[168:171], v[200:203], v[22:25]
	v_mfma_f32_16x16x32_bf16 v[18:21], v[176:179], v[200:203], v[18:21]
	v_mfma_f32_16x16x32_bf16 v[6:9], v[168:171], v[210:213], v[6:9]
	v_mfma_f32_16x16x32_bf16 v[2:5], v[176:179], v[210:213], v[2:5]
	s_barrier
	s_add_i32 s43, 0, 0x18000
	v_add_u32_e32 v149, s43, v146
	s_add_i32 s79, 0, 0x1c000
	ds_read_b128 v[142:145], v149
	ds_read_b128 v[152:155], v149 offset:1024
	ds_read_b128 v[156:159], v149 offset:2048
	ds_read_b128 v[160:163], v149 offset:3072
	v_add_u32_e32 v149, s79, v146
	ds_read_b128 v[164:167], v149
	ds_read_b128 v[168:171], v149 offset:1024
	ds_read_b128 v[172:175], v149 offset:2048
	ds_read_b128 v[176:179], v149 offset:3072
	s_add_u32 s40, s40, s12
	s_addc_u32 s41, s41, s13
	s_mov_b32 m0, s50
	v_lshl_add_u64 v[226:227], s[40:41], 0, v[134:135]
	ds_read_b128 v[180:183], v147 offset:32768
	ds_read_b128 v[184:187], v147 offset:33792
	ds_read_b128 v[188:191], v147 offset:34816
	ds_read_b128 v[192:195], v147 offset:35840
	ds_read_b128 v[196:199], v147 offset:36864
	ds_read_b128 v[200:203], v147 offset:37888
	ds_read_b128 v[204:207], v147 offset:38912
	ds_read_b128 v[210:213], v147 offset:39936
	global_load_lds_dwordx4 v[226:227], off
	v_lshl_add_u64 v[226:227], s[40:41], 0, v[136:137]
	s_mov_b32 m0, s51
	s_nop 0
	global_load_lds_dwordx4 v[226:227], off
	s_waitcnt vmcnt(8)
	s_waitcnt lgkmcnt(0)
	s_barrier
	s_waitcnt lgkmcnt(0)
	v_mfma_f32_16x16x32_bf16 v[126:129], v[142:145], v[180:183], v[126:129]
	v_mfma_f32_16x16x32_bf16 v[122:125], v[156:159], v[180:183], v[122:125]
	v_mfma_f32_16x16x32_bf16 v[110:113], v[142:145], v[188:191], v[110:113]
	v_mfma_f32_16x16x32_bf16 v[106:109], v[156:159], v[188:191], v[106:109]
	v_mfma_f32_16x16x32_bf16 v[94:97], v[142:145], v[196:199], v[94:97]
	v_mfma_f32_16x16x32_bf16 v[90:93], v[156:159], v[196:199], v[90:93]
	v_mfma_f32_16x16x32_bf16 v[78:81], v[142:145], v[204:207], v[78:81]
	v_mfma_f32_16x16x32_bf16 v[74:77], v[156:159], v[204:207], v[74:77]
	v_mfma_f32_16x16x32_bf16 v[126:129], v[152:155], v[184:187], v[126:129]
	v_mfma_f32_16x16x32_bf16 v[122:125], v[160:163], v[184:187], v[122:125]
	v_mfma_f32_16x16x32_bf16 v[110:113], v[152:155], v[192:195], v[110:113]
	v_mfma_f32_16x16x32_bf16 v[106:109], v[160:163], v[192:195], v[106:109]
	v_mfma_f32_16x16x32_bf16 v[94:97], v[152:155], v[200:203], v[94:97]
	v_mfma_f32_16x16x32_bf16 v[90:93], v[160:163], v[200:203], v[90:93]
	v_mfma_f32_16x16x32_bf16 v[78:81], v[152:155], v[210:213], v[78:81]
	v_mfma_f32_16x16x32_bf16 v[74:77], v[160:163], v[210:213], v[74:77]
	v_mfma_f32_16x16x32_bf16 v[118:121], v[164:167], v[180:183], v[118:121]
	v_mfma_f32_16x16x32_bf16 v[114:117], v[172:175], v[180:183], v[114:117]
	v_mfma_f32_16x16x32_bf16 v[102:105], v[164:167], v[188:191], v[102:105]
	v_mfma_f32_16x16x32_bf16 v[98:101], v[172:175], v[188:191], v[98:101]
	v_mfma_f32_16x16x32_bf16 v[86:89], v[164:167], v[196:199], v[86:89]
	v_mfma_f32_16x16x32_bf16 v[82:85], v[172:175], v[196:199], v[82:85]
	v_mfma_f32_16x16x32_bf16 v[70:73], v[164:167], v[204:207], v[70:73]
	v_mfma_f32_16x16x32_bf16 v[66:69], v[172:175], v[204:207], v[66:69]
	v_mfma_f32_16x16x32_bf16 v[118:121], v[168:171], v[184:187], v[118:121]
	v_mfma_f32_16x16x32_bf16 v[114:117], v[176:179], v[184:187], v[114:117]
	v_mfma_f32_16x16x32_bf16 v[102:105], v[168:171], v[192:195], v[102:105]
	v_mfma_f32_16x16x32_bf16 v[98:101], v[176:179], v[192:195], v[98:101]
	v_mfma_f32_16x16x32_bf16 v[86:89], v[168:171], v[200:203], v[86:89]
	v_mfma_f32_16x16x32_bf16 v[82:85], v[176:179], v[200:203], v[82:85]
	v_mfma_f32_16x16x32_bf16 v[70:73], v[168:171], v[210:213], v[70:73]
	v_mfma_f32_16x16x32_bf16 v[66:69], v[176:179], v[210:213], v[66:69]
	s_barrier
	s_add_i32 s40, s43, s45
	v_lshl_add_u64 v[214:215], v[214:215], 0, s[20:21]
	s_mov_b32 m0, s40
	ds_read_b128 v[180:183], v147 offset:49152
	ds_read_b128 v[184:187], v147 offset:50176
	ds_read_b128 v[188:191], v147 offset:51200
	ds_read_b128 v[192:195], v147 offset:52224
	ds_read_b128 v[196:199], v147 offset:53248
	ds_read_b128 v[200:203], v147 offset:54272
	ds_read_b128 v[204:207], v147 offset:55296
	ds_read_b128 v[210:213], v147 offset:56320
	global_load_lds_dwordx4 v[214:215], off
	v_lshl_add_u64 v[214:215], v[216:217], 0, s[20:21]
	s_add_i32 m0, s40, 0x2000
	s_add_i32 s40, s79, s45
	global_load_lds_dwordx4 v[214:215], off
	v_lshl_add_u64 v[214:215], v[218:219], 0, s[20:21]
	s_mov_b32 m0, s40
	s_nop 0
	global_load_lds_dwordx4 v[214:215], off
	v_lshl_add_u64 v[214:215], v[220:221], 0, s[20:21]
	s_add_i32 m0, s40, 0x2000
	s_nop 0
	global_load_lds_dwordx4 v[214:215], off
	v_lshl_add_u64 v[214:215], v[222:223], 0, s[20:21]
	s_mov_b32 m0, s56
	s_nop 0
	global_load_lds_dwordx4 v[214:215], off
	v_lshl_add_u64 v[214:215], v[224:225], 0, s[20:21]
	s_mov_b32 m0, s57
	s_nop 0
	global_load_lds_dwordx4 v[214:215], off
	s_waitcnt vmcnt(8)
	s_waitcnt lgkmcnt(0)
	s_barrier
	s_waitcnt lgkmcnt(0)
	v_mfma_f32_16x16x32_bf16 v[62:65], v[142:145], v[180:183], v[62:65]
	v_mfma_f32_16x16x32_bf16 v[58:61], v[156:159], v[180:183], v[58:61]
	v_mfma_f32_16x16x32_bf16 v[46:49], v[142:145], v[188:191], v[46:49]
	v_mfma_f32_16x16x32_bf16 v[42:45], v[156:159], v[188:191], v[42:45]
	v_mfma_f32_16x16x32_bf16 v[30:33], v[142:145], v[196:199], v[30:33]
	v_mfma_f32_16x16x32_bf16 v[26:29], v[156:159], v[196:199], v[26:29]
	v_mfma_f32_16x16x32_bf16 v[14:17], v[142:145], v[204:207], v[14:17]
	v_mfma_f32_16x16x32_bf16 v[10:13], v[156:159], v[204:207], v[10:13]
	v_mfma_f32_16x16x32_bf16 v[62:65], v[152:155], v[184:187], v[62:65]
	v_mfma_f32_16x16x32_bf16 v[58:61], v[160:163], v[184:187], v[58:61]
	v_mfma_f32_16x16x32_bf16 v[46:49], v[152:155], v[192:195], v[46:49]
	v_mfma_f32_16x16x32_bf16 v[42:45], v[160:163], v[192:195], v[42:45]
	v_mfma_f32_16x16x32_bf16 v[30:33], v[152:155], v[200:203], v[30:33]
	v_mfma_f32_16x16x32_bf16 v[26:29], v[160:163], v[200:203], v[26:29]
	v_mfma_f32_16x16x32_bf16 v[14:17], v[152:155], v[210:213], v[14:17]
	v_mfma_f32_16x16x32_bf16 v[10:13], v[160:163], v[210:213], v[10:13]
	v_mfma_f32_16x16x32_bf16 v[54:57], v[164:167], v[180:183], v[54:57]
	v_mfma_f32_16x16x32_bf16 v[50:53], v[172:175], v[180:183], v[50:53]
	v_mfma_f32_16x16x32_bf16 v[38:41], v[164:167], v[188:191], v[38:41]
	v_mfma_f32_16x16x32_bf16 v[34:37], v[172:175], v[188:191], v[34:37]
	v_mfma_f32_16x16x32_bf16 v[22:25], v[164:167], v[196:199], v[22:25]
	v_mfma_f32_16x16x32_bf16 v[18:21], v[172:175], v[196:199], v[18:21]
	v_mfma_f32_16x16x32_bf16 v[6:9], v[164:167], v[204:207], v[6:9]
	v_mfma_f32_16x16x32_bf16 v[2:5], v[172:175], v[204:207], v[2:5]
	v_mfma_f32_16x16x32_bf16 v[54:57], v[168:171], v[184:187], v[54:57]
	v_mfma_f32_16x16x32_bf16 v[50:53], v[176:179], v[184:187], v[50:53]
	v_mfma_f32_16x16x32_bf16 v[38:41], v[168:171], v[192:195], v[38:41]
	v_mfma_f32_16x16x32_bf16 v[34:37], v[176:179], v[192:195], v[34:37]
	v_mfma_f32_16x16x32_bf16 v[22:25], v[168:171], v[200:203], v[22:25]
	v_mfma_f32_16x16x32_bf16 v[18:21], v[176:179], v[200:203], v[18:21]
	v_mfma_f32_16x16x32_bf16 v[6:9], v[168:171], v[210:213], v[6:9]
	v_mfma_f32_16x16x32_bf16 v[2:5], v[176:179], v[210:213], v[2:5]
	s_barrier
	s_add_u32 s77, s77, 0x100
	s_addc_u32 s78, s78, 0
	s_add_u32 s4, s4, 0x100
	s_addc_u32 s5, s5, 0
	s_cmp_ge_i32 s42, s55
	s_mov_b32 s40, s42
	s_cbranch_scc0 .LBB0_1087

.LBB0_1199:
	ds_read_b128 v[144:147], v153
	ds_read_b128 v[158:161], v153 offset:1024
	ds_read_b128 v[162:165], v153 offset:2048
	ds_read_b128 v[166:169], v153 offset:3072
	ds_read_b128 v[170:173], v154
	ds_read_b128 v[174:177], v154 offset:1024
	ds_read_b128 v[178:181], v154 offset:2048
	ds_read_b128 v[182:185], v154 offset:3072
	s_add_i32 s74, s38, 2
	s_add_u32 s75, s36, 0x80
	s_addc_u32 s39, s37, 0
	s_cmp_eq_u32 s61, s38
	s_cselect_b32 s38, s4, s75
	s_cselect_b32 s39, s5, s39
	s_cselect_b32 s77, s25, s73
	s_cselect_b32 s76, s24, s72
	v_lshl_add_u64 v[148:149], s[36:37], 0, v[140:141]
	s_add_i32 m0, s51, 0xc000
	ds_read_b128 v[186:189], v155
	ds_read_b128 v[190:193], v155 offset:1024
	ds_read_b128 v[194:197], v155 offset:2048
	ds_read_b128 v[198:201], v155 offset:3072
	ds_read_b128 v[202:205], v155 offset:4096
	ds_read_b128 v[210:213], v155 offset:5120
	ds_read_b128 v[214:217], v155 offset:6144
	ds_read_b128 v[218:221], v155 offset:7168
	global_load_lds_dwordx4 v[148:149], off
	v_lshl_add_u64 v[148:149], s[36:37], 0, v[138:139]
	s_add_i32 m0, s51, 0xe000
	s_nop 0
	global_load_lds_dwordx4 v[148:149], off
	s_waitcnt vmcnt(8)
	s_waitcnt lgkmcnt(0)
	s_barrier
	s_waitcnt lgkmcnt(0)
	v_mfma_f32_16x16x32_bf16 v[122:125], v[144:147], v[186:189], v[122:125]
	v_mfma_f32_16x16x32_bf16 v[126:129], v[162:165], v[186:189], v[126:129]
	v_mfma_f32_16x16x32_bf16 v[110:113], v[144:147], v[194:197], v[110:113]
	v_mfma_f32_16x16x32_bf16 v[106:109], v[162:165], v[194:197], v[106:109]
	v_mfma_f32_16x16x32_bf16 v[94:97], v[144:147], v[202:205], v[94:97]
	v_mfma_f32_16x16x32_bf16 v[90:93], v[162:165], v[202:205], v[90:93]
	v_mfma_f32_16x16x32_bf16 v[78:81], v[144:147], v[214:217], v[78:81]
	v_mfma_f32_16x16x32_bf16 v[74:77], v[162:165], v[214:217], v[74:77]
	v_mfma_f32_16x16x32_bf16 v[122:125], v[158:161], v[190:193], v[122:125]
	v_mfma_f32_16x16x32_bf16 v[126:129], v[166:169], v[190:193], v[126:129]
	v_mfma_f32_16x16x32_bf16 v[110:113], v[158:161], v[198:201], v[110:113]
	v_mfma_f32_16x16x32_bf16 v[106:109], v[166:169], v[198:201], v[106:109]
	v_mfma_f32_16x16x32_bf16 v[94:97], v[158:161], v[210:213], v[94:97]
	v_mfma_f32_16x16x32_bf16 v[90:93], v[166:169], v[210:213], v[90:93]
	v_mfma_f32_16x16x32_bf16 v[78:81], v[158:161], v[218:221], v[78:81]
	v_mfma_f32_16x16x32_bf16 v[74:77], v[166:169], v[218:221], v[74:77]
	v_mfma_f32_16x16x32_bf16 v[118:121], v[170:173], v[186:189], v[118:121]
	v_mfma_f32_16x16x32_bf16 v[114:117], v[178:181], v[186:189], v[114:117]
	v_mfma_f32_16x16x32_bf16 v[102:105], v[170:173], v[194:197], v[102:105]
	v_mfma_f32_16x16x32_bf16 v[98:101], v[178:181], v[194:197], v[98:101]
	v_mfma_f32_16x16x32_bf16 v[86:89], v[170:173], v[202:205], v[86:89]
	v_mfma_f32_16x16x32_bf16 v[82:85], v[178:181], v[202:205], v[82:85]
	v_mfma_f32_16x16x32_bf16 v[70:73], v[170:173], v[214:217], v[70:73]
	v_mfma_f32_16x16x32_bf16 v[66:69], v[178:181], v[214:217], v[66:69]
	v_mfma_f32_16x16x32_bf16 v[118:121], v[174:177], v[190:193], v[118:121]
	v_mfma_f32_16x16x32_bf16 v[114:117], v[182:185], v[190:193], v[114:117]
	v_mfma_f32_16x16x32_bf16 v[102:105], v[174:177], v[198:201], v[102:105]
	v_mfma_f32_16x16x32_bf16 v[98:101], v[182:185], v[198:201], v[98:101]
	v_mfma_f32_16x16x32_bf16 v[86:89], v[174:177], v[210:213], v[86:89]
	v_mfma_f32_16x16x32_bf16 v[82:85], v[182:185], v[210:213], v[82:85]
	v_mfma_f32_16x16x32_bf16 v[70:73], v[174:177], v[218:221], v[70:73]
	v_mfma_f32_16x16x32_bf16 v[66:69], v[182:185], v[218:221], v[66:69]
	s_barrier
	s_add_i32 s75, s63, s48
	v_lshl_add_u64 v[148:149], s[76:77], 0, v[130:131]
	s_mov_b32 m0, s75
	ds_read_b128 v[186:189], v155 offset:16384
	ds_read_b128 v[190:193], v155 offset:17408
	ds_read_b128 v[194:197], v155 offset:18432
	ds_read_b128 v[198:201], v155 offset:19456
	ds_read_b128 v[202:205], v155 offset:20480
	ds_read_b128 v[210:213], v155 offset:21504
	ds_read_b128 v[214:217], v155 offset:22528
	ds_read_b128 v[218:221], v155 offset:23552
	global_load_lds_dwordx4 v[148:149], off
	s_add_i32 m0, s75, 0x2000
	v_lshl_add_u64 v[206:207], s[76:77], 0, v[132:133]
	s_add_u32 s76, s76, s10
	s_addc_u32 s77, s77, s11
	s_add_i32 s75, s64, s48
	global_load_lds_dwordx4 v[206:207], off
	v_lshl_add_u64 v[222:223], s[76:77], 0, v[130:131]
	s_mov_b32 m0, s75
	v_lshl_add_u64 v[224:225], s[76:77], 0, v[132:133]
	global_load_lds_dwordx4 v[222:223], off
	s_add_i32 m0, s75, 0x2000
	v_lshl_add_u64 v[226:227], s[38:39], 0, v[134:135]
	global_load_lds_dwordx4 v[224:225], off
	s_mov_b32 m0, s51
	v_lshl_add_u64 v[228:229], s[38:39], 0, v[136:137]
	global_load_lds_dwordx4 v[226:227], off
	s_mov_b32 m0, s52
	s_nop 0
	global_load_lds_dwordx4 v[228:229], off
	s_waitcnt vmcnt(8)
	s_waitcnt lgkmcnt(0)
	s_barrier
	s_waitcnt lgkmcnt(0)
	v_mfma_f32_16x16x32_bf16 v[62:65], v[144:147], v[186:189], v[62:65]
	v_mfma_f32_16x16x32_bf16 v[58:61], v[162:165], v[186:189], v[58:61]
	v_mfma_f32_16x16x32_bf16 v[46:49], v[144:147], v[194:197], v[46:49]
	v_mfma_f32_16x16x32_bf16 v[42:45], v[162:165], v[194:197], v[42:45]
	v_mfma_f32_16x16x32_bf16 v[30:33], v[144:147], v[202:205], v[30:33]
	v_mfma_f32_16x16x32_bf16 v[26:29], v[162:165], v[202:205], v[26:29]
	v_mfma_f32_16x16x32_bf16 v[14:17], v[144:147], v[214:217], v[14:17]
	v_mfma_f32_16x16x32_bf16 v[10:13], v[162:165], v[214:217], v[10:13]
	v_mfma_f32_16x16x32_bf16 v[62:65], v[158:161], v[190:193], v[62:65]
	v_mfma_f32_16x16x32_bf16 v[58:61], v[166:169], v[190:193], v[58:61]
	v_mfma_f32_16x16x32_bf16 v[46:49], v[158:161], v[198:201], v[46:49]
	v_mfma_f32_16x16x32_bf16 v[42:45], v[166:169], v[198:201], v[42:45]
	v_mfma_f32_16x16x32_bf16 v[30:33], v[158:161], v[210:213], v[30:33]
	v_mfma_f32_16x16x32_bf16 v[26:29], v[166:169], v[210:213], v[26:29]
	v_mfma_f32_16x16x32_bf16 v[14:17], v[158:161], v[218:221], v[14:17]
	v_mfma_f32_16x16x32_bf16 v[10:13], v[166:169], v[218:221], v[10:13]
	v_mfma_f32_16x16x32_bf16 v[54:57], v[170:173], v[186:189], v[54:57]
	v_mfma_f32_16x16x32_bf16 v[50:53], v[178:181], v[186:189], v[50:53]
	v_mfma_f32_16x16x32_bf16 v[38:41], v[170:173], v[194:197], v[38:41]
	v_mfma_f32_16x16x32_bf16 v[34:37], v[178:181], v[194:197], v[34:37]
	v_mfma_f32_16x16x32_bf16 v[22:25], v[170:173], v[202:205], v[22:25]
	v_mfma_f32_16x16x32_bf16 v[18:21], v[178:181], v[202:205], v[18:21]
	v_mfma_f32_16x16x32_bf16 v[6:9], v[170:173], v[214:217], v[6:9]
	v_mfma_f32_16x16x32_bf16 v[2:5], v[178:181], v[214:217], v[2:5]
	v_mfma_f32_16x16x32_bf16 v[54:57], v[174:177], v[190:193], v[54:57]
	v_mfma_f32_16x16x32_bf16 v[50:53], v[182:185], v[190:193], v[50:53]
	v_mfma_f32_16x16x32_bf16 v[38:41], v[174:177], v[198:201], v[38:41]
	v_mfma_f32_16x16x32_bf16 v[34:37], v[182:185], v[198:201], v[34:37]
	v_mfma_f32_16x16x32_bf16 v[22:25], v[174:177], v[210:213], v[22:25]
	v_mfma_f32_16x16x32_bf16 v[18:21], v[182:185], v[210:213], v[18:21]
	v_mfma_f32_16x16x32_bf16 v[6:9], v[174:177], v[218:221], v[6:9]
	v_mfma_f32_16x16x32_bf16 v[2:5], v[182:185], v[218:221], v[2:5]
	s_barrier
	s_add_i32 s75, 0, 0x18000
	v_add_u32_e32 v157, s75, v152
	s_add_i32 s76, 0, 0x1c000
	ds_read_b128 v[144:147], v157
	ds_read_b128 v[158:161], v157 offset:1024
	ds_read_b128 v[162:165], v157 offset:2048
	ds_read_b128 v[166:169], v157 offset:3072
	v_add_u32_e32 v157, s76, v152
	ds_read_b128 v[170:173], v157
	ds_read_b128 v[174:177], v157 offset:1024
	ds_read_b128 v[178:181], v157 offset:2048
	ds_read_b128 v[182:185], v157 offset:3072
	s_add_u32 s38, s38, s10
	s_addc_u32 s39, s39, s11
	s_mov_b32 m0, s53
	v_lshl_add_u64 v[230:231], s[38:39], 0, v[134:135]
	ds_read_b128 v[186:189], v155 offset:32768
	ds_read_b128 v[190:193], v155 offset:33792
	ds_read_b128 v[194:197], v155 offset:34816
	ds_read_b128 v[198:201], v155 offset:35840
	ds_read_b128 v[202:205], v155 offset:36864
	ds_read_b128 v[210:213], v155 offset:37888
	ds_read_b128 v[214:217], v155 offset:38912
	ds_read_b128 v[218:221], v155 offset:39936
	global_load_lds_dwordx4 v[230:231], off
	v_lshl_add_u64 v[230:231], s[38:39], 0, v[136:137]
	s_mov_b32 m0, s54
	s_nop 0
	global_load_lds_dwordx4 v[230:231], off
	s_waitcnt vmcnt(8)
	s_waitcnt lgkmcnt(0)
	s_barrier
	s_waitcnt lgkmcnt(0)
	v_mfma_f32_16x16x32_bf16 v[122:125], v[144:147], v[186:189], v[122:125]
	v_mfma_f32_16x16x32_bf16 v[126:129], v[162:165], v[186:189], v[126:129]
	v_mfma_f32_16x16x32_bf16 v[110:113], v[144:147], v[194:197], v[110:113]
	v_mfma_f32_16x16x32_bf16 v[106:109], v[162:165], v[194:197], v[106:109]
	v_mfma_f32_16x16x32_bf16 v[94:97], v[144:147], v[202:205], v[94:97]
	v_mfma_f32_16x16x32_bf16 v[90:93], v[162:165], v[202:205], v[90:93]
	v_mfma_f32_16x16x32_bf16 v[78:81], v[144:147], v[214:217], v[78:81]
	v_mfma_f32_16x16x32_bf16 v[74:77], v[162:165], v[214:217], v[74:77]
	v_mfma_f32_16x16x32_bf16 v[122:125], v[158:161], v[190:193], v[122:125]
	v_mfma_f32_16x16x32_bf16 v[126:129], v[166:169], v[190:193], v[126:129]
	v_mfma_f32_16x16x32_bf16 v[110:113], v[158:161], v[198:201], v[110:113]
	v_mfma_f32_16x16x32_bf16 v[106:109], v[166:169], v[198:201], v[106:109]
	v_mfma_f32_16x16x32_bf16 v[94:97], v[158:161], v[210:213], v[94:97]
	v_mfma_f32_16x16x32_bf16 v[90:93], v[166:169], v[210:213], v[90:93]
	v_mfma_f32_16x16x32_bf16 v[78:81], v[158:161], v[218:221], v[78:81]
	v_mfma_f32_16x16x32_bf16 v[74:77], v[166:169], v[218:221], v[74:77]
	v_mfma_f32_16x16x32_bf16 v[118:121], v[170:173], v[186:189], v[118:121]
	v_mfma_f32_16x16x32_bf16 v[114:117], v[178:181], v[186:189], v[114:117]
	v_mfma_f32_16x16x32_bf16 v[102:105], v[170:173], v[194:197], v[102:105]
	v_mfma_f32_16x16x32_bf16 v[98:101], v[178:181], v[194:197], v[98:101]
	v_mfma_f32_16x16x32_bf16 v[86:89], v[170:173], v[202:205], v[86:89]
	v_mfma_f32_16x16x32_bf16 v[82:85], v[178:181], v[202:205], v[82:85]
	v_mfma_f32_16x16x32_bf16 v[70:73], v[170:173], v[214:217], v[70:73]
	v_mfma_f32_16x16x32_bf16 v[66:69], v[178:181], v[214:217], v[66:69]
	v_mfma_f32_16x16x32_bf16 v[118:121], v[174:177], v[190:193], v[118:121]
	v_mfma_f32_16x16x32_bf16 v[114:117], v[182:185], v[190:193], v[114:117]
	v_mfma_f32_16x16x32_bf16 v[102:105], v[174:177], v[198:201], v[102:105]
	v_mfma_f32_16x16x32_bf16 v[98:101], v[182:185], v[198:201], v[98:101]
	v_mfma_f32_16x16x32_bf16 v[86:89], v[174:177], v[210:213], v[86:89]
	v_mfma_f32_16x16x32_bf16 v[82:85], v[182:185], v[210:213], v[82:85]
	v_mfma_f32_16x16x32_bf16 v[70:73], v[174:177], v[218:221], v[70:73]
	v_mfma_f32_16x16x32_bf16 v[66:69], v[182:185], v[218:221], v[66:69]
	s_barrier
	s_add_i32 s38, s75, s48
	v_lshl_add_u64 v[148:149], v[148:149], 0, s[18:19]
	s_mov_b32 m0, s38
	ds_read_b128 v[186:189], v155 offset:49152
	ds_read_b128 v[190:193], v155 offset:50176
	ds_read_b128 v[194:197], v155 offset:51200
	ds_read_b128 v[198:201], v155 offset:52224
	ds_read_b128 v[202:205], v155 offset:53248
	ds_read_b128 v[210:213], v155 offset:54272
	ds_read_b128 v[214:217], v155 offset:55296
	ds_read_b128 v[218:221], v155 offset:56320
	global_load_lds_dwordx4 v[148:149], off
	v_lshl_add_u64 v[148:149], v[206:207], 0, s[18:19]
	s_add_i32 m0, s38, 0x2000
	s_add_i32 s38, s76, s48
	global_load_lds_dwordx4 v[148:149], off
	v_lshl_add_u64 v[148:149], v[222:223], 0, s[18:19]
	s_mov_b32 m0, s38
	s_nop 0
	global_load_lds_dwordx4 v[148:149], off
	v_lshl_add_u64 v[148:149], v[224:225], 0, s[18:19]
	s_add_i32 m0, s38, 0x2000
	s_nop 0
	global_load_lds_dwordx4 v[148:149], off
	v_lshl_add_u64 v[148:149], v[226:227], 0, s[18:19]
	s_mov_b32 m0, s57
	s_nop 0
	global_load_lds_dwordx4 v[148:149], off
	v_lshl_add_u64 v[148:149], v[228:229], 0, s[18:19]
	s_mov_b32 m0, s58
	s_nop 0
	global_load_lds_dwordx4 v[148:149], off
	s_waitcnt vmcnt(8)
	s_waitcnt lgkmcnt(0)
	s_barrier
	s_waitcnt lgkmcnt(0)
	v_mfma_f32_16x16x32_bf16 v[62:65], v[144:147], v[186:189], v[62:65]
	v_mfma_f32_16x16x32_bf16 v[58:61], v[162:165], v[186:189], v[58:61]
	v_mfma_f32_16x16x32_bf16 v[46:49], v[144:147], v[194:197], v[46:49]
	v_mfma_f32_16x16x32_bf16 v[42:45], v[162:165], v[194:197], v[42:45]
	v_mfma_f32_16x16x32_bf16 v[30:33], v[144:147], v[202:205], v[30:33]
	v_mfma_f32_16x16x32_bf16 v[26:29], v[162:165], v[202:205], v[26:29]
	v_mfma_f32_16x16x32_bf16 v[14:17], v[144:147], v[214:217], v[14:17]
	v_mfma_f32_16x16x32_bf16 v[10:13], v[162:165], v[214:217], v[10:13]
	v_mfma_f32_16x16x32_bf16 v[62:65], v[158:161], v[190:193], v[62:65]
	v_mfma_f32_16x16x32_bf16 v[58:61], v[166:169], v[190:193], v[58:61]
	v_mfma_f32_16x16x32_bf16 v[46:49], v[158:161], v[198:201], v[46:49]
	v_mfma_f32_16x16x32_bf16 v[42:45], v[166:169], v[198:201], v[42:45]
	v_mfma_f32_16x16x32_bf16 v[30:33], v[158:161], v[210:213], v[30:33]
	v_mfma_f32_16x16x32_bf16 v[26:29], v[166:169], v[210:213], v[26:29]
	v_mfma_f32_16x16x32_bf16 v[14:17], v[158:161], v[218:221], v[14:17]
	v_mfma_f32_16x16x32_bf16 v[10:13], v[166:169], v[218:221], v[10:13]
	v_mfma_f32_16x16x32_bf16 v[54:57], v[170:173], v[186:189], v[54:57]
	v_mfma_f32_16x16x32_bf16 v[50:53], v[178:181], v[186:189], v[50:53]
	v_mfma_f32_16x16x32_bf16 v[38:41], v[170:173], v[194:197], v[38:41]
	v_mfma_f32_16x16x32_bf16 v[34:37], v[178:181], v[194:197], v[34:37]
	v_mfma_f32_16x16x32_bf16 v[22:25], v[170:173], v[202:205], v[22:25]
	v_mfma_f32_16x16x32_bf16 v[18:21], v[178:181], v[202:205], v[18:21]
	v_mfma_f32_16x16x32_bf16 v[6:9], v[170:173], v[214:217], v[6:9]
	v_mfma_f32_16x16x32_bf16 v[2:5], v[178:181], v[214:217], v[2:5]
	v_mfma_f32_16x16x32_bf16 v[54:57], v[174:177], v[190:193], v[54:57]
	v_mfma_f32_16x16x32_bf16 v[50:53], v[182:185], v[190:193], v[50:53]
	v_mfma_f32_16x16x32_bf16 v[38:41], v[174:177], v[198:201], v[38:41]
	v_mfma_f32_16x16x32_bf16 v[34:37], v[182:185], v[198:201], v[34:37]
	v_mfma_f32_16x16x32_bf16 v[22:25], v[174:177], v[210:213], v[22:25]
	v_mfma_f32_16x16x32_bf16 v[18:21], v[182:185], v[210:213], v[18:21]
	v_mfma_f32_16x16x32_bf16 v[6:9], v[174:177], v[218:221], v[6:9]
	v_mfma_f32_16x16x32_bf16 v[2:5], v[182:185], v[218:221], v[2:5]
	s_barrier
	s_add_u32 s72, s72, 0x100
	s_addc_u32 s73, s73, 0
	s_add_u32 s36, s36, 0x100
	s_addc_u32 s37, s37, 0
	s_cmp_ge_i32 s74, s56
	s_mov_b32 s38, s74
	s_cbranch_scc0 .LBB0_1199

.LBB0_1297:
	v_add_u32_e32 v149, s67, v146
	ds_read_b128 v[142:145], v149
	ds_read_b128 v[152:155], v149 offset:1024
	ds_read_b128 v[156:159], v149 offset:2048
	ds_read_b128 v[160:163], v149 offset:3072
	v_add_u32_e32 v149, s70, v146
	ds_read_b128 v[164:167], v149
	ds_read_b128 v[168:171], v149 offset:1024
	ds_read_b128 v[172:175], v149 offset:2048
	ds_read_b128 v[176:179], v149 offset:3072
	s_add_i32 s42, s40, 2
	s_add_u32 s43, s4, 0x80
	s_addc_u32 s41, s5, 0
	s_cmp_eq_u32 s56, s40
	s_cselect_b32 s40, s36, s43
	s_cselect_b32 s41, s37, s41
	s_cselect_b32 s79, s39, s76
	s_cselect_b32 s78, s38, s75
	v_lshl_add_u64 v[214:215], s[4:5], 0, v[140:141]
	s_add_i32 m0, s48, 0xc000
	ds_read_b128 v[180:183], v147
	ds_read_b128 v[184:187], v147 offset:1024
	ds_read_b128 v[188:191], v147 offset:2048
	ds_read_b128 v[192:195], v147 offset:3072
	ds_read_b128 v[196:199], v147 offset:4096
	ds_read_b128 v[200:203], v147 offset:5120
	ds_read_b128 v[204:207], v147 offset:6144
	ds_read_b128 v[210:213], v147 offset:7168
	global_load_lds_dwordx4 v[214:215], off
	v_lshl_add_u64 v[214:215], s[4:5], 0, v[138:139]
	s_add_i32 m0, s48, 0xe000
	s_nop 0
	global_load_lds_dwordx4 v[214:215], off
	s_waitcnt vmcnt(8)
	s_waitcnt lgkmcnt(0)
	s_barrier
	s_waitcnt lgkmcnt(0)
	v_mfma_f32_16x16x32_bf16 v[118:121], v[142:145], v[180:183], v[118:121]
	v_mfma_f32_16x16x32_bf16 v[122:125], v[156:159], v[180:183], v[122:125]
	v_mfma_f32_16x16x32_bf16 v[94:97], v[142:145], v[188:191], v[94:97]
	v_mfma_f32_16x16x32_bf16 v[106:109], v[156:159], v[188:191], v[106:109]
	v_mfma_f32_16x16x32_bf16 v[78:81], v[142:145], v[196:199], v[78:81]
	v_mfma_f32_16x16x32_bf16 v[90:93], v[156:159], v[196:199], v[90:93]
	v_mfma_f32_16x16x32_bf16 v[54:57], v[142:145], v[204:207], v[54:57]
	v_mfma_f32_16x16x32_bf16 v[74:77], v[156:159], v[204:207], v[74:77]
	v_mfma_f32_16x16x32_bf16 v[118:121], v[152:155], v[184:187], v[118:121]
	v_mfma_f32_16x16x32_bf16 v[122:125], v[160:163], v[184:187], v[122:125]
	v_mfma_f32_16x16x32_bf16 v[94:97], v[152:155], v[192:195], v[94:97]
	v_mfma_f32_16x16x32_bf16 v[106:109], v[160:163], v[192:195], v[106:109]
	v_mfma_f32_16x16x32_bf16 v[78:81], v[152:155], v[200:203], v[78:81]
	v_mfma_f32_16x16x32_bf16 v[90:93], v[160:163], v[200:203], v[90:93]
	v_mfma_f32_16x16x32_bf16 v[54:57], v[152:155], v[210:213], v[54:57]
	v_mfma_f32_16x16x32_bf16 v[74:77], v[160:163], v[210:213], v[74:77]
	v_mfma_f32_16x16x32_bf16 v[114:117], v[164:167], v[180:183], v[114:117]
	v_mfma_f32_16x16x32_bf16 v[126:129], v[172:175], v[180:183], v[126:129]
	v_mfma_f32_16x16x32_bf16 v[102:105], v[164:167], v[188:191], v[102:105]
	v_mfma_f32_16x16x32_bf16 v[110:113], v[172:175], v[188:191], v[110:113]
	v_mfma_f32_16x16x32_bf16 v[86:89], v[164:167], v[196:199], v[86:89]
	v_mfma_f32_16x16x32_bf16 v[98:101], v[172:175], v[196:199], v[98:101]
	v_mfma_f32_16x16x32_bf16 v[70:73], v[164:167], v[204:207], v[70:73]
	v_mfma_f32_16x16x32_bf16 v[82:85], v[172:175], v[204:207], v[82:85]
	v_mfma_f32_16x16x32_bf16 v[114:117], v[168:171], v[184:187], v[114:117]
	v_mfma_f32_16x16x32_bf16 v[126:129], v[176:179], v[184:187], v[126:129]
	v_mfma_f32_16x16x32_bf16 v[102:105], v[168:171], v[192:195], v[102:105]
	v_mfma_f32_16x16x32_bf16 v[110:113], v[176:179], v[192:195], v[110:113]
	v_mfma_f32_16x16x32_bf16 v[86:89], v[168:171], v[200:203], v[86:89]
	v_mfma_f32_16x16x32_bf16 v[98:101], v[176:179], v[200:203], v[98:101]
	v_mfma_f32_16x16x32_bf16 v[70:73], v[168:171], v[210:213], v[70:73]
	v_mfma_f32_16x16x32_bf16 v[82:85], v[176:179], v[210:213], v[82:85]
	s_barrier
	s_add_i32 s43, s67, s45
	v_lshl_add_u64 v[214:215], s[78:79], 0, v[130:131]
	s_mov_b32 m0, s43
	ds_read_b128 v[180:183], v147 offset:16384
	ds_read_b128 v[184:187], v147 offset:17408
	ds_read_b128 v[188:191], v147 offset:18432
	ds_read_b128 v[192:195], v147 offset:19456
	ds_read_b128 v[196:199], v147 offset:20480
	ds_read_b128 v[200:203], v147 offset:21504
	ds_read_b128 v[204:207], v147 offset:22528
	ds_read_b128 v[210:213], v147 offset:23552
	global_load_lds_dwordx4 v[214:215], off
	s_add_i32 m0, s43, 0x2000
	v_lshl_add_u64 v[216:217], s[78:79], 0, v[132:133]
	s_add_u32 s78, s78, s14
	s_addc_u32 s79, s79, s15
	s_add_i32 s43, s70, s45
	global_load_lds_dwordx4 v[216:217], off
	v_lshl_add_u64 v[218:219], s[78:79], 0, v[130:131]
	s_mov_b32 m0, s43
	v_lshl_add_u64 v[220:221], s[78:79], 0, v[132:133]
	global_load_lds_dwordx4 v[218:219], off
	s_add_i32 m0, s43, 0x2000
	v_lshl_add_u64 v[222:223], s[40:41], 0, v[134:135]
	global_load_lds_dwordx4 v[220:221], off
	s_mov_b32 m0, s48
	v_lshl_add_u64 v[224:225], s[40:41], 0, v[136:137]
	global_load_lds_dwordx4 v[222:223], off
	s_mov_b32 m0, s49
	s_nop 0
	global_load_lds_dwordx4 v[224:225], off
	s_waitcnt vmcnt(8)
	s_waitcnt lgkmcnt(0)
	s_barrier
	s_waitcnt lgkmcnt(0)
	v_mfma_f32_16x16x32_bf16 v[30:33], v[142:145], v[180:183], v[30:33]
	v_mfma_f32_16x16x32_bf16 v[42:45], v[156:159], v[180:183], v[42:45]
	v_mfma_f32_16x16x32_bf16 v[14:17], v[142:145], v[188:191], v[14:17]
	v_mfma_f32_16x16x32_bf16 v[26:29], v[156:159], v[188:191], v[26:29]
	v_mfma_f32_16x16x32_bf16 v[2:5], v[142:145], v[196:199], v[2:5]
	v_mfma_f32_16x16x32_bf16 v[10:13], v[156:159], v[196:199], v[10:13]
	v_mfma_f32_16x16x32_bf16 v[50:53], v[142:145], v[204:207], v[50:53]
	v_mfma_f32_16x16x32_bf16 v[58:61], v[156:159], v[204:207], v[58:61]
	v_mfma_f32_16x16x32_bf16 v[30:33], v[152:155], v[184:187], v[30:33]
	v_mfma_f32_16x16x32_bf16 v[42:45], v[160:163], v[184:187], v[42:45]
	v_mfma_f32_16x16x32_bf16 v[14:17], v[152:155], v[192:195], v[14:17]
	v_mfma_f32_16x16x32_bf16 v[26:29], v[160:163], v[192:195], v[26:29]
	v_mfma_f32_16x16x32_bf16 v[2:5], v[152:155], v[200:203], v[2:5]
	v_mfma_f32_16x16x32_bf16 v[10:13], v[160:163], v[200:203], v[10:13]
	v_mfma_f32_16x16x32_bf16 v[50:53], v[152:155], v[210:213], v[50:53]
	v_mfma_f32_16x16x32_bf16 v[58:61], v[160:163], v[210:213], v[58:61]
	v_mfma_f32_16x16x32_bf16 v[38:41], v[164:167], v[180:183], v[38:41]
	v_mfma_f32_16x16x32_bf16 v[62:65], v[172:175], v[180:183], v[62:65]
	v_mfma_f32_16x16x32_bf16 v[22:25], v[164:167], v[188:191], v[22:25]
	v_mfma_f32_16x16x32_bf16 v[34:37], v[172:175], v[188:191], v[34:37]
	v_mfma_f32_16x16x32_bf16 v[6:9], v[164:167], v[196:199], v[6:9]
	v_mfma_f32_16x16x32_bf16 v[18:21], v[172:175], v[196:199], v[18:21]
	v_mfma_f32_16x16x32_bf16 v[46:49], v[164:167], v[204:207], v[46:49]
	v_mfma_f32_16x16x32_bf16 v[66:69], v[172:175], v[204:207], v[66:69]
	v_mfma_f32_16x16x32_bf16 v[38:41], v[168:171], v[184:187], v[38:41]
	v_mfma_f32_16x16x32_bf16 v[62:65], v[176:179], v[184:187], v[62:65]
	v_mfma_f32_16x16x32_bf16 v[22:25], v[168:171], v[192:195], v[22:25]
	v_mfma_f32_16x16x32_bf16 v[34:37], v[176:179], v[192:195], v[34:37]
	v_mfma_f32_16x16x32_bf16 v[6:9], v[168:171], v[200:203], v[6:9]
	v_mfma_f32_16x16x32_bf16 v[18:21], v[176:179], v[200:203], v[18:21]
	v_mfma_f32_16x16x32_bf16 v[46:49], v[168:171], v[210:213], v[46:49]
	v_mfma_f32_16x16x32_bf16 v[66:69], v[176:179], v[210:213], v[66:69]
	s_barrier
	s_add_i32 s43, 0, 0x18000
	v_add_u32_e32 v149, s43, v146
	s_add_i32 s77, 0, 0x1c000
	ds_read_b128 v[142:145], v149
	ds_read_b128 v[152:155], v149 offset:1024
	ds_read_b128 v[156:159], v149 offset:2048
	ds_read_b128 v[160:163], v149 offset:3072
	v_add_u32_e32 v149, s77, v146
	ds_read_b128 v[164:167], v149
	ds_read_b128 v[168:171], v149 offset:1024
	ds_read_b128 v[172:175], v149 offset:2048
	ds_read_b128 v[176:179], v149 offset:3072
	s_add_u32 s40, s40, s14
	s_addc_u32 s41, s41, s15
	s_mov_b32 m0, s50
	v_lshl_add_u64 v[226:227], s[40:41], 0, v[134:135]
	ds_read_b128 v[180:183], v147 offset:32768
	ds_read_b128 v[184:187], v147 offset:33792
	ds_read_b128 v[188:191], v147 offset:34816
	ds_read_b128 v[192:195], v147 offset:35840
	ds_read_b128 v[196:199], v147 offset:36864
	ds_read_b128 v[200:203], v147 offset:37888
	ds_read_b128 v[204:207], v147 offset:38912
	ds_read_b128 v[210:213], v147 offset:39936
	global_load_lds_dwordx4 v[226:227], off
	v_lshl_add_u64 v[226:227], s[40:41], 0, v[136:137]
	s_mov_b32 m0, s51
	s_nop 0
	global_load_lds_dwordx4 v[226:227], off
	s_waitcnt vmcnt(8)
	s_waitcnt lgkmcnt(0)
	s_barrier
	s_waitcnt lgkmcnt(0)
	v_mfma_f32_16x16x32_bf16 v[118:121], v[142:145], v[180:183], v[118:121]
	v_mfma_f32_16x16x32_bf16 v[122:125], v[156:159], v[180:183], v[122:125]
	v_mfma_f32_16x16x32_bf16 v[94:97], v[142:145], v[188:191], v[94:97]
	v_mfma_f32_16x16x32_bf16 v[106:109], v[156:159], v[188:191], v[106:109]
	v_mfma_f32_16x16x32_bf16 v[78:81], v[142:145], v[196:199], v[78:81]
	v_mfma_f32_16x16x32_bf16 v[90:93], v[156:159], v[196:199], v[90:93]
	v_mfma_f32_16x16x32_bf16 v[54:57], v[142:145], v[204:207], v[54:57]
	v_mfma_f32_16x16x32_bf16 v[74:77], v[156:159], v[204:207], v[74:77]
	v_mfma_f32_16x16x32_bf16 v[118:121], v[152:155], v[184:187], v[118:121]
	v_mfma_f32_16x16x32_bf16 v[122:125], v[160:163], v[184:187], v[122:125]
	v_mfma_f32_16x16x32_bf16 v[94:97], v[152:155], v[192:195], v[94:97]
	v_mfma_f32_16x16x32_bf16 v[106:109], v[160:163], v[192:195], v[106:109]
	v_mfma_f32_16x16x32_bf16 v[78:81], v[152:155], v[200:203], v[78:81]
	v_mfma_f32_16x16x32_bf16 v[90:93], v[160:163], v[200:203], v[90:93]
	v_mfma_f32_16x16x32_bf16 v[54:57], v[152:155], v[210:213], v[54:57]
	v_mfma_f32_16x16x32_bf16 v[74:77], v[160:163], v[210:213], v[74:77]
	v_mfma_f32_16x16x32_bf16 v[114:117], v[164:167], v[180:183], v[114:117]
	v_mfma_f32_16x16x32_bf16 v[126:129], v[172:175], v[180:183], v[126:129]
	v_mfma_f32_16x16x32_bf16 v[102:105], v[164:167], v[188:191], v[102:105]
	v_mfma_f32_16x16x32_bf16 v[110:113], v[172:175], v[188:191], v[110:113]
	v_mfma_f32_16x16x32_bf16 v[86:89], v[164:167], v[196:199], v[86:89]
	v_mfma_f32_16x16x32_bf16 v[98:101], v[172:175], v[196:199], v[98:101]
	v_mfma_f32_16x16x32_bf16 v[70:73], v[164:167], v[204:207], v[70:73]
	v_mfma_f32_16x16x32_bf16 v[82:85], v[172:175], v[204:207], v[82:85]
	v_mfma_f32_16x16x32_bf16 v[114:117], v[168:171], v[184:187], v[114:117]
	v_mfma_f32_16x16x32_bf16 v[126:129], v[176:179], v[184:187], v[126:129]
	v_mfma_f32_16x16x32_bf16 v[102:105], v[168:171], v[192:195], v[102:105]
	v_mfma_f32_16x16x32_bf16 v[110:113], v[176:179], v[192:195], v[110:113]
	v_mfma_f32_16x16x32_bf16 v[86:89], v[168:171], v[200:203], v[86:89]
	v_mfma_f32_16x16x32_bf16 v[98:101], v[176:179], v[200:203], v[98:101]
	v_mfma_f32_16x16x32_bf16 v[70:73], v[168:171], v[210:213], v[70:73]
	v_mfma_f32_16x16x32_bf16 v[82:85], v[176:179], v[210:213], v[82:85]
	s_barrier
	s_add_i32 s40, s43, s45
	v_lshl_add_u64 v[214:215], v[214:215], 0, s[20:21]
	s_mov_b32 m0, s40
	ds_read_b128 v[180:183], v147 offset:49152
	ds_read_b128 v[184:187], v147 offset:50176
	ds_read_b128 v[188:191], v147 offset:51200
	ds_read_b128 v[192:195], v147 offset:52224
	ds_read_b128 v[196:199], v147 offset:53248
	ds_read_b128 v[200:203], v147 offset:54272
	ds_read_b128 v[204:207], v147 offset:55296
	ds_read_b128 v[210:213], v147 offset:56320
	global_load_lds_dwordx4 v[214:215], off
	v_lshl_add_u64 v[214:215], v[216:217], 0, s[20:21]
	s_add_i32 m0, s40, 0x2000
	s_add_i32 s40, s77, s45
	global_load_lds_dwordx4 v[214:215], off
	v_lshl_add_u64 v[214:215], v[218:219], 0, s[20:21]
	s_mov_b32 m0, s40
	s_nop 0
	global_load_lds_dwordx4 v[214:215], off
	v_lshl_add_u64 v[214:215], v[220:221], 0, s[20:21]
	s_add_i32 m0, s40, 0x2000
	s_nop 0
	global_load_lds_dwordx4 v[214:215], off
	v_lshl_add_u64 v[214:215], v[222:223], 0, s[20:21]
	s_mov_b32 m0, s54
	s_nop 0
	global_load_lds_dwordx4 v[214:215], off
	v_lshl_add_u64 v[214:215], v[224:225], 0, s[20:21]
	s_mov_b32 m0, s55
	s_nop 0
	global_load_lds_dwordx4 v[214:215], off
	s_waitcnt vmcnt(8)
	s_waitcnt lgkmcnt(0)
	s_barrier
	s_waitcnt lgkmcnt(0)
	v_mfma_f32_16x16x32_bf16 v[30:33], v[142:145], v[180:183], v[30:33]
	v_mfma_f32_16x16x32_bf16 v[42:45], v[156:159], v[180:183], v[42:45]
	v_mfma_f32_16x16x32_bf16 v[14:17], v[142:145], v[188:191], v[14:17]
	v_mfma_f32_16x16x32_bf16 v[26:29], v[156:159], v[188:191], v[26:29]
	v_mfma_f32_16x16x32_bf16 v[2:5], v[142:145], v[196:199], v[2:5]
	v_mfma_f32_16x16x32_bf16 v[10:13], v[156:159], v[196:199], v[10:13]
	v_mfma_f32_16x16x32_bf16 v[50:53], v[142:145], v[204:207], v[50:53]
	v_mfma_f32_16x16x32_bf16 v[58:61], v[156:159], v[204:207], v[58:61]
	v_mfma_f32_16x16x32_bf16 v[30:33], v[152:155], v[184:187], v[30:33]
	v_mfma_f32_16x16x32_bf16 v[42:45], v[160:163], v[184:187], v[42:45]
	v_mfma_f32_16x16x32_bf16 v[14:17], v[152:155], v[192:195], v[14:17]
	v_mfma_f32_16x16x32_bf16 v[26:29], v[160:163], v[192:195], v[26:29]
	v_mfma_f32_16x16x32_bf16 v[2:5], v[152:155], v[200:203], v[2:5]
	v_mfma_f32_16x16x32_bf16 v[10:13], v[160:163], v[200:203], v[10:13]
	v_mfma_f32_16x16x32_bf16 v[50:53], v[152:155], v[210:213], v[50:53]
	v_mfma_f32_16x16x32_bf16 v[58:61], v[160:163], v[210:213], v[58:61]
	v_mfma_f32_16x16x32_bf16 v[38:41], v[164:167], v[180:183], v[38:41]
	v_mfma_f32_16x16x32_bf16 v[62:65], v[172:175], v[180:183], v[62:65]
	v_mfma_f32_16x16x32_bf16 v[22:25], v[164:167], v[188:191], v[22:25]
	v_mfma_f32_16x16x32_bf16 v[34:37], v[172:175], v[188:191], v[34:37]
	v_mfma_f32_16x16x32_bf16 v[6:9], v[164:167], v[196:199], v[6:9]
	v_mfma_f32_16x16x32_bf16 v[18:21], v[172:175], v[196:199], v[18:21]
	v_mfma_f32_16x16x32_bf16 v[46:49], v[164:167], v[204:207], v[46:49]
	v_mfma_f32_16x16x32_bf16 v[66:69], v[172:175], v[204:207], v[66:69]
	v_mfma_f32_16x16x32_bf16 v[38:41], v[168:171], v[184:187], v[38:41]
	v_mfma_f32_16x16x32_bf16 v[62:65], v[176:179], v[184:187], v[62:65]
	v_mfma_f32_16x16x32_bf16 v[22:25], v[168:171], v[192:195], v[22:25]
	v_mfma_f32_16x16x32_bf16 v[34:37], v[176:179], v[192:195], v[34:37]
	v_mfma_f32_16x16x32_bf16 v[6:9], v[168:171], v[200:203], v[6:9]
	v_mfma_f32_16x16x32_bf16 v[18:21], v[176:179], v[200:203], v[18:21]
	v_mfma_f32_16x16x32_bf16 v[46:49], v[168:171], v[210:213], v[46:49]
	v_mfma_f32_16x16x32_bf16 v[66:69], v[176:179], v[210:213], v[66:69]
	s_barrier
	s_add_u32 s75, s75, 0x100
	s_addc_u32 s76, s76, 0
	s_add_u32 s4, s4, 0x100
	s_addc_u32 s5, s5, 0
	s_cmp_ge_i32 s42, s53
	s_mov_b32 s40, s42
	s_cbranch_scc0 .LBB0_1297

.LBB0_1446:
	s_add_i32 s36, s44, 2
	ds_read_b128 v[140:143], v192
	ds_read_b128 v[144:147], v192 offset:1024
	ds_read_b128 v[148:151], v192 offset:2048
	ds_read_b128 v[152:155], v192 offset:3072
	ds_read_b128 v[156:159], v193
	ds_read_b128 v[160:163], v193 offset:1024
	ds_read_b128 v[164:167], v193 offset:2048
	ds_read_b128 v[168:171], v193 offset:3072
	s_or_b32 s72, s44, 1
	s_lshl_b64 s[74:75], s[36:37], 7
	s_add_u32 s71, s0, s74
	s_addc_u32 s45, s1, s75
	s_cmp_eq_u32 s44, s55
	s_cselect_b32 s74, 0, s74
	s_mov_b32 s73, s37
	s_cselect_b32 s45, s43, s45
	s_cselect_b32 s44, s42, s71
	s_cselect_b32 s71, 0, s75
	s_add_u32 s74, s22, s74
	s_addc_u32 s75, s23, s71
	s_lshl_b64 s[72:73], s[72:73], 7
	s_add_u32 s72, s69, s72
	s_addc_u32 s73, s70, s73
	s_mov_b32 m0, s56
	v_lshl_add_u64 v[188:189], s[72:73], 0, v[134:135]
	ds_read_b128 v[172:175], v194
	ds_read_b128 v[176:179], v194 offset:1024
	ds_read_b128 v[180:183], v194 offset:2048
	ds_read_b128 v[184:187], v194 offset:3072
	ds_read_b128 v[200:203], v194 offset:4096
	ds_read_b128 v[204:207], v194 offset:5120
	ds_read_b128 v[210:213], v194 offset:6144
	ds_read_b128 v[214:217], v194 offset:7168
	global_load_lds_dwordx4 v[188:189], off
	v_lshl_add_u64 v[188:189], s[72:73], 0, v[136:137]
	s_mov_b32 m0, s57
	s_nop 0
	global_load_lds_dwordx4 v[188:189], off
	s_waitcnt vmcnt(8)
	s_waitcnt lgkmcnt(0)
	s_barrier
	s_waitcnt lgkmcnt(0)
	v_mfma_f32_16x16x32_bf16 v[126:129], v[140:143], v[172:175], v[126:129]
	v_mfma_f32_16x16x32_bf16 v[122:125], v[148:151], v[172:175], v[122:125]
	v_mfma_f32_16x16x32_bf16 v[110:113], v[140:143], v[180:183], v[110:113]
	v_mfma_f32_16x16x32_bf16 v[106:109], v[148:151], v[180:183], v[106:109]
	v_mfma_f32_16x16x32_bf16 v[94:97], v[140:143], v[200:203], v[94:97]
	v_mfma_f32_16x16x32_bf16 v[90:93], v[148:151], v[200:203], v[90:93]
	v_mfma_f32_16x16x32_bf16 v[78:81], v[140:143], v[210:213], v[78:81]
	v_mfma_f32_16x16x32_bf16 v[74:77], v[148:151], v[210:213], v[74:77]
	v_mfma_f32_16x16x32_bf16 v[126:129], v[144:147], v[176:179], v[126:129]
	v_mfma_f32_16x16x32_bf16 v[122:125], v[152:155], v[176:179], v[122:125]
	v_mfma_f32_16x16x32_bf16 v[110:113], v[144:147], v[184:187], v[110:113]
	v_mfma_f32_16x16x32_bf16 v[106:109], v[152:155], v[184:187], v[106:109]
	v_mfma_f32_16x16x32_bf16 v[94:97], v[144:147], v[204:207], v[94:97]
	v_mfma_f32_16x16x32_bf16 v[90:93], v[152:155], v[204:207], v[90:93]
	v_mfma_f32_16x16x32_bf16 v[78:81], v[144:147], v[214:217], v[78:81]
	v_mfma_f32_16x16x32_bf16 v[74:77], v[152:155], v[214:217], v[74:77]
	v_mfma_f32_16x16x32_bf16 v[118:121], v[156:159], v[172:175], v[118:121]
	v_mfma_f32_16x16x32_bf16 v[114:117], v[164:167], v[172:175], v[114:117]
	v_mfma_f32_16x16x32_bf16 v[102:105], v[156:159], v[180:183], v[102:105]
	v_mfma_f32_16x16x32_bf16 v[98:101], v[164:167], v[180:183], v[98:101]
	v_mfma_f32_16x16x32_bf16 v[86:89], v[156:159], v[200:203], v[86:89]
	v_mfma_f32_16x16x32_bf16 v[82:85], v[164:167], v[200:203], v[82:85]
	v_mfma_f32_16x16x32_bf16 v[70:73], v[156:159], v[210:213], v[70:73]
	v_mfma_f32_16x16x32_bf16 v[66:69], v[164:167], v[210:213], v[66:69]
	v_mfma_f32_16x16x32_bf16 v[118:121], v[160:163], v[176:179], v[118:121]
	v_mfma_f32_16x16x32_bf16 v[114:117], v[168:171], v[176:179], v[114:117]
	v_mfma_f32_16x16x32_bf16 v[102:105], v[160:163], v[184:187], v[102:105]
	v_mfma_f32_16x16x32_bf16 v[98:101], v[168:171], v[184:187], v[98:101]
	v_mfma_f32_16x16x32_bf16 v[86:89], v[160:163], v[204:207], v[86:89]
	v_mfma_f32_16x16x32_bf16 v[82:85], v[168:171], v[204:207], v[82:85]
	v_mfma_f32_16x16x32_bf16 v[70:73], v[160:163], v[214:217], v[70:73]
	v_mfma_f32_16x16x32_bf16 v[66:69], v[168:171], v[214:217], v[66:69]
	s_barrier
	s_mov_b32 m0, s58
	v_lshl_add_u64 v[188:189], s[74:75], 0, v[130:131]
	s_add_u32 s72, s74, s24
	ds_read_b128 v[172:175], v194 offset:16384
	ds_read_b128 v[176:179], v194 offset:17408
	ds_read_b128 v[180:183], v194 offset:18432
	ds_read_b128 v[184:187], v194 offset:19456
	ds_read_b128 v[200:203], v194 offset:20480
	ds_read_b128 v[204:207], v194 offset:21504
	ds_read_b128 v[210:213], v194 offset:22528
	ds_read_b128 v[214:217], v194 offset:23552
	global_load_lds_dwordx4 v[188:189], off
	v_lshl_add_u64 v[218:219], s[74:75], 0, v[132:133]
	s_mov_b32 m0, s59
	s_addc_u32 s73, s75, s25
	global_load_lds_dwordx4 v[218:219], off
	v_lshl_add_u64 v[220:221], s[72:73], 0, v[130:131]
	s_mov_b32 m0, s60
	v_lshl_add_u64 v[222:223], s[72:73], 0, v[132:133]
	global_load_lds_dwordx4 v[220:221], off
	s_mov_b32 m0, s61
	v_lshl_add_u64 v[224:225], s[44:45], 0, v[134:135]
	global_load_lds_dwordx4 v[222:223], off
	s_mov_b32 m0, s33
	v_lshl_add_u64 v[226:227], s[44:45], 0, v[136:137]
	global_load_lds_dwordx4 v[224:225], off
	s_mov_b32 m0, s35
	s_nop 0
	global_load_lds_dwordx4 v[226:227], off
	s_waitcnt vmcnt(8)
	s_waitcnt lgkmcnt(0)
	s_barrier
	s_waitcnt lgkmcnt(0)
	v_mfma_f32_16x16x32_bf16 v[62:65], v[140:143], v[172:175], v[62:65]
	v_mfma_f32_16x16x32_bf16 v[58:61], v[148:151], v[172:175], v[58:61]
	v_mfma_f32_16x16x32_bf16 v[46:49], v[140:143], v[180:183], v[46:49]
	v_mfma_f32_16x16x32_bf16 v[42:45], v[148:151], v[180:183], v[42:45]
	v_mfma_f32_16x16x32_bf16 v[30:33], v[140:143], v[200:203], v[30:33]
	v_mfma_f32_16x16x32_bf16 v[26:29], v[148:151], v[200:203], v[26:29]
	v_mfma_f32_16x16x32_bf16 v[14:17], v[140:143], v[210:213], v[14:17]
	v_mfma_f32_16x16x32_bf16 v[10:13], v[148:151], v[210:213], v[10:13]
	v_mfma_f32_16x16x32_bf16 v[62:65], v[144:147], v[176:179], v[62:65]
	v_mfma_f32_16x16x32_bf16 v[58:61], v[152:155], v[176:179], v[58:61]
	v_mfma_f32_16x16x32_bf16 v[46:49], v[144:147], v[184:187], v[46:49]
	v_mfma_f32_16x16x32_bf16 v[42:45], v[152:155], v[184:187], v[42:45]
	v_mfma_f32_16x16x32_bf16 v[30:33], v[144:147], v[204:207], v[30:33]
	v_mfma_f32_16x16x32_bf16 v[26:29], v[152:155], v[204:207], v[26:29]
	v_mfma_f32_16x16x32_bf16 v[14:17], v[144:147], v[214:217], v[14:17]
	v_mfma_f32_16x16x32_bf16 v[10:13], v[152:155], v[214:217], v[10:13]
	v_mfma_f32_16x16x32_bf16 v[54:57], v[156:159], v[172:175], v[54:57]
	v_mfma_f32_16x16x32_bf16 v[50:53], v[164:167], v[172:175], v[50:53]
	v_mfma_f32_16x16x32_bf16 v[38:41], v[156:159], v[180:183], v[38:41]
	v_mfma_f32_16x16x32_bf16 v[34:37], v[164:167], v[180:183], v[34:37]
	v_mfma_f32_16x16x32_bf16 v[22:25], v[156:159], v[200:203], v[22:25]
	v_mfma_f32_16x16x32_bf16 v[18:21], v[164:167], v[200:203], v[18:21]
	v_mfma_f32_16x16x32_bf16 v[6:9], v[156:159], v[210:213], v[6:9]
	v_mfma_f32_16x16x32_bf16 v[2:5], v[164:167], v[210:213], v[2:5]
	v_mfma_f32_16x16x32_bf16 v[54:57], v[160:163], v[176:179], v[54:57]
	v_mfma_f32_16x16x32_bf16 v[50:53], v[168:171], v[176:179], v[50:53]
	v_mfma_f32_16x16x32_bf16 v[38:41], v[160:163], v[184:187], v[38:41]
	v_mfma_f32_16x16x32_bf16 v[34:37], v[168:171], v[184:187], v[34:37]
	v_mfma_f32_16x16x32_bf16 v[22:25], v[160:163], v[204:207], v[22:25]
	v_mfma_f32_16x16x32_bf16 v[18:21], v[168:171], v[204:207], v[18:21]
	v_mfma_f32_16x16x32_bf16 v[6:9], v[160:163], v[214:217], v[6:9]
	v_mfma_f32_16x16x32_bf16 v[2:5], v[168:171], v[214:217], v[2:5]
	s_barrier
	ds_read_b128 v[140:143], v195
	ds_read_b128 v[144:147], v195 offset:1024
	ds_read_b128 v[148:151], v195 offset:2048
	ds_read_b128 v[152:155], v195 offset:3072
	ds_read_b128 v[156:159], v196
	ds_read_b128 v[160:163], v196 offset:1024
	ds_read_b128 v[164:167], v196 offset:2048
	ds_read_b128 v[168:171], v196 offset:3072
	s_add_u32 s44, s44, s24
	s_addc_u32 s45, s45, s25
	s_mov_b32 m0, s46
	v_lshl_add_u64 v[228:229], s[44:45], 0, v[134:135]
	ds_read_b128 v[172:175], v194 offset:32768
	ds_read_b128 v[176:179], v194 offset:33792
	ds_read_b128 v[180:183], v194 offset:34816
	ds_read_b128 v[184:187], v194 offset:35840
	ds_read_b128 v[200:203], v194 offset:36864
	ds_read_b128 v[204:207], v194 offset:37888
	ds_read_b128 v[210:213], v194 offset:38912
	ds_read_b128 v[214:217], v194 offset:39936
	global_load_lds_dwordx4 v[228:229], off
	v_lshl_add_u64 v[228:229], s[44:45], 0, v[136:137]
	s_mov_b32 m0, s47
	s_nop 0
	global_load_lds_dwordx4 v[228:229], off
	s_waitcnt vmcnt(8)
	s_waitcnt lgkmcnt(0)
	s_barrier
	s_waitcnt lgkmcnt(0)
	v_mfma_f32_16x16x32_bf16 v[126:129], v[140:143], v[172:175], v[126:129]
	v_mfma_f32_16x16x32_bf16 v[122:125], v[148:151], v[172:175], v[122:125]
	v_mfma_f32_16x16x32_bf16 v[110:113], v[140:143], v[180:183], v[110:113]
	v_mfma_f32_16x16x32_bf16 v[106:109], v[148:151], v[180:183], v[106:109]
	v_mfma_f32_16x16x32_bf16 v[94:97], v[140:143], v[200:203], v[94:97]
	v_mfma_f32_16x16x32_bf16 v[90:93], v[148:151], v[200:203], v[90:93]
	v_mfma_f32_16x16x32_bf16 v[78:81], v[140:143], v[210:213], v[78:81]
	v_mfma_f32_16x16x32_bf16 v[74:77], v[148:151], v[210:213], v[74:77]
	v_mfma_f32_16x16x32_bf16 v[126:129], v[144:147], v[176:179], v[126:129]
	v_mfma_f32_16x16x32_bf16 v[122:125], v[152:155], v[176:179], v[122:125]
	v_mfma_f32_16x16x32_bf16 v[110:113], v[144:147], v[184:187], v[110:113]
	v_mfma_f32_16x16x32_bf16 v[106:109], v[152:155], v[184:187], v[106:109]
	v_mfma_f32_16x16x32_bf16 v[94:97], v[144:147], v[204:207], v[94:97]
	v_mfma_f32_16x16x32_bf16 v[90:93], v[152:155], v[204:207], v[90:93]
	v_mfma_f32_16x16x32_bf16 v[78:81], v[144:147], v[214:217], v[78:81]
	v_mfma_f32_16x16x32_bf16 v[74:77], v[152:155], v[214:217], v[74:77]
	v_mfma_f32_16x16x32_bf16 v[118:121], v[156:159], v[172:175], v[118:121]
	v_mfma_f32_16x16x32_bf16 v[114:117], v[164:167], v[172:175], v[114:117]
	v_mfma_f32_16x16x32_bf16 v[102:105], v[156:159], v[180:183], v[102:105]
	v_mfma_f32_16x16x32_bf16 v[98:101], v[164:167], v[180:183], v[98:101]
	v_mfma_f32_16x16x32_bf16 v[86:89], v[156:159], v[200:203], v[86:89]
	v_mfma_f32_16x16x32_bf16 v[82:85], v[164:167], v[200:203], v[82:85]
	v_mfma_f32_16x16x32_bf16 v[70:73], v[156:159], v[210:213], v[70:73]
	v_mfma_f32_16x16x32_bf16 v[66:69], v[164:167], v[210:213], v[66:69]
	v_mfma_f32_16x16x32_bf16 v[118:121], v[160:163], v[176:179], v[118:121]
	v_mfma_f32_16x16x32_bf16 v[114:117], v[168:171], v[176:179], v[114:117]
	v_mfma_f32_16x16x32_bf16 v[102:105], v[160:163], v[184:187], v[102:105]
	v_mfma_f32_16x16x32_bf16 v[98:101], v[168:171], v[184:187], v[98:101]
	v_mfma_f32_16x16x32_bf16 v[86:89], v[160:163], v[204:207], v[86:89]
	v_mfma_f32_16x16x32_bf16 v[82:85], v[168:171], v[204:207], v[82:85]
	v_mfma_f32_16x16x32_bf16 v[70:73], v[160:163], v[214:217], v[70:73]
	v_mfma_f32_16x16x32_bf16 v[66:69], v[168:171], v[214:217], v[66:69]
	s_barrier
	s_mov_b32 m0, s62
	v_lshl_add_u64 v[188:189], v[188:189], 0, s[18:19]
	ds_read_b128 v[172:175], v194 offset:49152
	ds_read_b128 v[176:179], v194 offset:50176
	ds_read_b128 v[180:183], v194 offset:51200
	ds_read_b128 v[184:187], v194 offset:52224
	ds_read_b128 v[200:203], v194 offset:53248
	ds_read_b128 v[204:207], v194 offset:54272
	ds_read_b128 v[210:213], v194 offset:55296
	ds_read_b128 v[214:217], v194 offset:56320
	global_load_lds_dwordx4 v[188:189], off
	v_lshl_add_u64 v[188:189], v[218:219], 0, s[18:19]
	s_mov_b32 m0, s63
	s_nop 0
	global_load_lds_dwordx4 v[188:189], off
	v_lshl_add_u64 v[188:189], v[220:221], 0, s[18:19]
	s_mov_b32 m0, s64
	s_nop 0
	global_load_lds_dwordx4 v[188:189], off
	v_lshl_add_u64 v[188:189], v[222:223], 0, s[18:19]
	s_mov_b32 m0, s65
	s_nop 0
	global_load_lds_dwordx4 v[188:189], off
	v_lshl_add_u64 v[188:189], v[224:225], 0, s[18:19]
	s_mov_b32 m0, s50
	s_nop 0
	global_load_lds_dwordx4 v[188:189], off
	v_lshl_add_u64 v[188:189], v[226:227], 0, s[18:19]
	s_mov_b32 m0, s51
	s_nop 0
	global_load_lds_dwordx4 v[188:189], off
	s_waitcnt vmcnt(8)
	s_waitcnt lgkmcnt(0)
	s_barrier
	s_waitcnt lgkmcnt(0)
	v_mfma_f32_16x16x32_bf16 v[62:65], v[140:143], v[172:175], v[62:65]
	v_mfma_f32_16x16x32_bf16 v[58:61], v[148:151], v[172:175], v[58:61]
	v_mfma_f32_16x16x32_bf16 v[46:49], v[140:143], v[180:183], v[46:49]
	v_mfma_f32_16x16x32_bf16 v[42:45], v[148:151], v[180:183], v[42:45]
	v_mfma_f32_16x16x32_bf16 v[30:33], v[140:143], v[200:203], v[30:33]
	v_mfma_f32_16x16x32_bf16 v[26:29], v[148:151], v[200:203], v[26:29]
	v_mfma_f32_16x16x32_bf16 v[14:17], v[140:143], v[210:213], v[14:17]
	v_mfma_f32_16x16x32_bf16 v[10:13], v[148:151], v[210:213], v[10:13]
	v_mfma_f32_16x16x32_bf16 v[62:65], v[144:147], v[176:179], v[62:65]
	v_mfma_f32_16x16x32_bf16 v[58:61], v[152:155], v[176:179], v[58:61]
	v_mfma_f32_16x16x32_bf16 v[46:49], v[144:147], v[184:187], v[46:49]
	v_mfma_f32_16x16x32_bf16 v[42:45], v[152:155], v[184:187], v[42:45]
	v_mfma_f32_16x16x32_bf16 v[30:33], v[144:147], v[204:207], v[30:33]
	v_mfma_f32_16x16x32_bf16 v[26:29], v[152:155], v[204:207], v[26:29]
	v_mfma_f32_16x16x32_bf16 v[14:17], v[144:147], v[214:217], v[14:17]
	v_mfma_f32_16x16x32_bf16 v[10:13], v[152:155], v[214:217], v[10:13]
	v_mfma_f32_16x16x32_bf16 v[54:57], v[156:159], v[172:175], v[54:57]
	v_mfma_f32_16x16x32_bf16 v[50:53], v[164:167], v[172:175], v[50:53]
	v_mfma_f32_16x16x32_bf16 v[38:41], v[156:159], v[180:183], v[38:41]
	v_mfma_f32_16x16x32_bf16 v[34:37], v[164:167], v[180:183], v[34:37]
	v_mfma_f32_16x16x32_bf16 v[22:25], v[156:159], v[200:203], v[22:25]
	v_mfma_f32_16x16x32_bf16 v[18:21], v[164:167], v[200:203], v[18:21]
	v_mfma_f32_16x16x32_bf16 v[6:9], v[156:159], v[210:213], v[6:9]
	v_mfma_f32_16x16x32_bf16 v[2:5], v[164:167], v[210:213], v[2:5]
	v_mfma_f32_16x16x32_bf16 v[54:57], v[160:163], v[176:179], v[54:57]
	v_mfma_f32_16x16x32_bf16 v[50:53], v[168:171], v[176:179], v[50:53]
	v_mfma_f32_16x16x32_bf16 v[38:41], v[160:163], v[184:187], v[38:41]
	v_mfma_f32_16x16x32_bf16 v[34:37], v[168:171], v[184:187], v[34:37]
	v_mfma_f32_16x16x32_bf16 v[22:25], v[160:163], v[204:207], v[22:25]
	v_mfma_f32_16x16x32_bf16 v[18:21], v[168:171], v[204:207], v[18:21]
	v_mfma_f32_16x16x32_bf16 v[6:9], v[160:163], v[214:217], v[6:9]
	v_mfma_f32_16x16x32_bf16 v[2:5], v[168:171], v[214:217], v[2:5]
	s_barrier
	s_cmp_ge_i32 s36, s54
	s_mov_b32 s44, s36
	s_cbranch_scc0 .LBB0_1446
	v_readlane_b32 s72, v235, 8
	v_readlane_b32 s74, v235, 10
	v_readlane_b32 s75, v235, 11
	v_readlane_b32 s86, v235, 22
	v_readlane_b32 s87, v235, 23
	s_mov_b64 s[74:75], s[86:87]
	v_readlane_b32 s73, v235, 9
	v_readlane_b32 s76, v235, 12
	v_readlane_b32 s77, v235, 13
	v_readlane_b32 s78, v235, 14
	v_readlane_b32 s79, v235, 15
	v_readlane_b32 s80, v235, 16
	v_readlane_b32 s81, v235, 17
	v_readlane_b32 s82, v235, 18
	v_readlane_b32 s83, v235, 19
	v_readlane_b32 s84, v235, 20
	v_readlane_b32 s85, v235, 21
